# MIXB/MB 8x64 blocked layout (full-line EpiSS stores) + sc1 on P6 and P9 output stores, plus the v111 policies
# baseline (speedup 1.0000x reference)
.LBB0_729:
	v_mul_f32_e32 v157, v125, v125
	v_mul_f32_e32 v160, v127, v127
	v_fmac_f32_e32 v157, v124, v124
	v_fmac_f32_e32 v160, v126, v126
	v_add_f32_e32 v157, v157, v160
	v_mul_f32_e32 v160, v121, v121
	v_fmac_f32_e32 v160, v120, v120
	v_cvt_pk_bf16_f32 v124, v124, v125
	v_cvt_pk_bf16_f32 v125, v126, v127
	v_cvt_pk_bf16_f32 v126, v120, v121
	v_mul_f32_e32 v120, v117, v117
	v_mul_f32_e32 v121, v119, v119
	v_fmac_f32_e32 v120, v116, v116
	v_fmac_f32_e32 v121, v118, v118
	v_add_f32_e32 v120, v120, v121
	v_mul_f32_e32 v121, v113, v113
	v_and_b32_e32 v155, 64, v154
	v_fmac_f32_e32 v121, v112, v112
	v_xor_b32_e32 v147, 16, v154
	v_add_u32_e32 v155, 64, v155
	v_add_f32_e32 v157, v157, v160
	v_mul_f32_e32 v160, v123, v123
	v_add_f32_e32 v120, v120, v121
	v_mul_f32_e32 v121, v115, v115
	v_cmp_lt_i32_e32 vcc, v147, v155
	v_fmac_f32_e32 v160, v122, v122
	v_fmac_f32_e32 v121, v114, v114
	v_cndmask_b32_e32 v147, v154, v147, vcc
	v_add_f32_e32 v157, v160, v157
	v_add_f32_e32 v120, v121, v120
	v_lshlrev_b32_e32 v156, 2, v147
	v_xor_b32_e32 v147, 32, v154
	v_cvt_pk_bf16_f32 v127, v122, v123
	v_add_f32_e32 v122, v157, v120
	v_cmp_lt_i32_e32 vcc, v147, v155
	ds_bpermute_b32 v123, v156, v122
	v_lshl_add_u32 v146, s28, 8, v148
	v_cndmask_b32_e32 v147, v154, v147, vcc
	v_lshlrev_b32_e32 v155, 2, v147
	v_ashrrev_i32_e32 v147, 31, v146
	v_and_b32_e32 v214, 0x40, v150
	v_and_b32_e32 v215, 0x38, v150
	v_lshlrev_b32_e32 v214, 7, v214
	v_lshl_or_b32 v214, v215, 1, v214
	v_and_b32_e32 v215, 7, v148
	v_mul_u32_u24_e32 v215, 0x780, v215
	v_sub_u32_e32 v214, v214, v215
	v_lshl_add_u32 v144, s12, 11, v214
	v_lshlrev_b64 v[158:159], 11, v[146:147]
	v_ashrrev_i32_e32 v145, 31, v144
	v_lshl_add_u64 v[120:121], s[8:9], 0, v[158:159]
	v_lshl_add_u64 v[158:159], v[144:145], 0, v[120:121]
	v_cvt_pk_bf16_f32 v120, v116, v117
	s_waitcnt lgkmcnt(0)
	v_add_f32_e32 v116, v122, v123
	ds_bpermute_b32 v117, v155, v116
	s_lshl_b32 s28, s12, 2
	s_ashr_i32 s29, s28, 31
	v_cvt_pk_bf16_f32 v121, v118, v119
	v_cvt_pk_bf16_f32 v122, v112, v113
	v_cvt_pk_bf16_f32 v123, v114, v115
	global_store_dwordx4 v[158:159], v[124:127], off sc1
	global_store_dwordx4 v[158:159], v[120:123], off offset:1024 sc1
	s_and_saveexec_b64 s[30:31], s[4:5]
	s_cbranch_execz .LBB0_731
	v_lshlrev_b64 v[112:113], 6, v[146:147]
	v_lshl_add_u64 v[112:113], s[10:11], 0, v[112:113]
	v_lshl_add_u64 v[112:113], s[28:29], 2, v[112:113]
	s_lshl_b32 s12, s43, 2
	s_waitcnt lgkmcnt(0)
	v_add_f32_e32 v114, v116, v117
	v_lshl_add_u64 v[112:113], v[112:113], 0, s[12:13]
	global_store_dword v[112:113], v114, off
.LBB0_731:
	s_or_b64 exec, exec, s[30:31]
	v_mul_f32_e32 v116, v109, v109
	s_waitcnt lgkmcnt(0)
	v_mul_f32_e32 v117, v111, v111
	v_fmac_f32_e32 v116, v108, v108
	v_fmac_f32_e32 v117, v110, v110
	v_add_f32_e32 v116, v116, v117
	v_mul_f32_e32 v117, v105, v105
	v_fmac_f32_e32 v117, v104, v104
	v_cvt_pk_bf16_f32 v108, v108, v109
	v_cvt_pk_bf16_f32 v109, v110, v111
	v_cvt_pk_bf16_f32 v110, v104, v105
	v_mul_f32_e32 v104, v101, v101
	v_mul_f32_e32 v105, v103, v103
	v_fmac_f32_e32 v104, v100, v100
	v_fmac_f32_e32 v105, v102, v102
	v_add_f32_e32 v104, v104, v105
	v_mul_f32_e32 v105, v97, v97
	v_fmac_f32_e32 v105, v96, v96
	v_add_f32_e32 v116, v116, v117
	v_mul_f32_e32 v117, v107, v107
	v_add_f32_e32 v104, v104, v105
	v_mul_f32_e32 v105, v99, v99
	v_fmac_f32_e32 v117, v106, v106
	v_fmac_f32_e32 v105, v98, v98
	v_add_f32_e32 v116, v117, v116
	v_add_f32_e32 v104, v105, v104
	v_cvt_pk_bf16_f32 v111, v106, v107
	v_add_f32_e32 v106, v116, v104
	ds_bpermute_b32 v107, v156, v106
	v_or_b32_e32 v112, 16, v146
	v_ashrrev_i32_e32 v113, 31, v112
	v_lshlrev_b64 v[114:115], 11, v[112:113]
	v_lshl_add_u64 v[104:105], s[8:9], 0, v[114:115]
	v_lshl_add_u64 v[114:115], v[144:145], 0, v[104:105]
	v_cvt_pk_bf16_f32 v104, v100, v101
	s_waitcnt lgkmcnt(0)
	v_add_f32_e32 v100, v106, v107
	ds_bpermute_b32 v101, v155, v100
	v_cvt_pk_bf16_f32 v105, v102, v103
	v_cvt_pk_bf16_f32 v106, v96, v97
	v_cvt_pk_bf16_f32 v107, v98, v99
	global_store_dwordx4 v[114:115], v[108:111], off sc1
	global_store_dwordx4 v[114:115], v[104:107], off offset:1024 sc1
	s_and_saveexec_b64 s[30:31], s[4:5]
	s_cbranch_execz .LBB0_733
	v_lshlrev_b64 v[96:97], 6, v[112:113]
	v_lshl_add_u64 v[96:97], s[10:11], 0, v[96:97]
	v_lshl_add_u64 v[96:97], s[28:29], 2, v[96:97]
	s_lshl_b32 s12, s43, 2
	s_waitcnt lgkmcnt(0)
	v_add_f32_e32 v98, v100, v101
	v_lshl_add_u64 v[96:97], v[96:97], 0, s[12:13]
	global_store_dword v[96:97], v98, off
.LBB0_733:
	s_or_b64 exec, exec, s[30:31]
	v_mul_f32_e32 v100, v93, v93
	s_waitcnt lgkmcnt(0)
	v_mul_f32_e32 v101, v95, v95
	v_fmac_f32_e32 v100, v92, v92
	v_fmac_f32_e32 v101, v94, v94
	v_add_f32_e32 v100, v100, v101
	v_mul_f32_e32 v101, v89, v89
	v_fmac_f32_e32 v101, v88, v88
	v_cvt_pk_bf16_f32 v92, v92, v93
	v_cvt_pk_bf16_f32 v93, v94, v95
	v_cvt_pk_bf16_f32 v94, v88, v89
	v_mul_f32_e32 v88, v85, v85
	v_mul_f32_e32 v89, v87, v87
	v_fmac_f32_e32 v88, v84, v84
	v_fmac_f32_e32 v89, v86, v86
	v_add_f32_e32 v88, v88, v89
	v_mul_f32_e32 v89, v81, v81
	v_fmac_f32_e32 v89, v80, v80
	v_add_f32_e32 v100, v100, v101
	v_mul_f32_e32 v101, v91, v91
	v_add_f32_e32 v88, v88, v89
	v_mul_f32_e32 v89, v83, v83
	v_fmac_f32_e32 v101, v90, v90
	v_fmac_f32_e32 v89, v82, v82
	v_add_f32_e32 v100, v101, v100
	v_add_f32_e32 v88, v89, v88
	v_cvt_pk_bf16_f32 v95, v90, v91
	v_add_f32_e32 v90, v100, v88
	ds_bpermute_b32 v91, v156, v90
	v_or_b32_e32 v96, 32, v146
	v_ashrrev_i32_e32 v97, 31, v96
	v_lshlrev_b64 v[98:99], 11, v[96:97]
	v_lshl_add_u64 v[88:89], s[8:9], 0, v[98:99]
	v_lshl_add_u64 v[98:99], v[144:145], 0, v[88:89]
	v_cvt_pk_bf16_f32 v88, v84, v85
	s_waitcnt lgkmcnt(0)
	v_add_f32_e32 v84, v90, v91
	ds_bpermute_b32 v85, v155, v84
	v_cvt_pk_bf16_f32 v89, v86, v87
	v_cvt_pk_bf16_f32 v90, v80, v81
	v_cvt_pk_bf16_f32 v91, v82, v83
	global_store_dwordx4 v[98:99], v[92:95], off sc1
	global_store_dwordx4 v[98:99], v[88:91], off offset:1024 sc1
	s_and_saveexec_b64 s[30:31], s[4:5]
	s_cbranch_execz .LBB0_735
	v_lshlrev_b64 v[80:81], 6, v[96:97]
	v_lshl_add_u64 v[80:81], s[10:11], 0, v[80:81]
	v_lshl_add_u64 v[80:81], s[28:29], 2, v[80:81]
	s_lshl_b32 s12, s43, 2
	s_waitcnt lgkmcnt(0)
	v_add_f32_e32 v82, v84, v85
	v_lshl_add_u64 v[80:81], v[80:81], 0, s[12:13]
	global_store_dword v[80:81], v82, off
.LBB0_735:
	s_or_b64 exec, exec, s[30:31]
	v_mul_f32_e32 v84, v77, v77
	s_waitcnt lgkmcnt(0)
	v_mul_f32_e32 v85, v79, v79
	v_fmac_f32_e32 v84, v76, v76
	v_fmac_f32_e32 v85, v78, v78
	v_add_f32_e32 v84, v84, v85
	v_mul_f32_e32 v85, v73, v73
	v_fmac_f32_e32 v85, v72, v72
	v_cvt_pk_bf16_f32 v76, v76, v77
	v_cvt_pk_bf16_f32 v77, v78, v79
	v_cvt_pk_bf16_f32 v78, v72, v73
	v_mul_f32_e32 v72, v69, v69
	v_mul_f32_e32 v73, v71, v71
	v_fmac_f32_e32 v72, v68, v68
	v_fmac_f32_e32 v73, v70, v70
	v_add_f32_e32 v72, v72, v73
	v_mul_f32_e32 v73, v65, v65
	v_fmac_f32_e32 v73, v64, v64
	v_add_f32_e32 v84, v84, v85
	v_mul_f32_e32 v85, v75, v75
	v_add_f32_e32 v72, v72, v73
	v_mul_f32_e32 v73, v67, v67
	v_fmac_f32_e32 v85, v74, v74
	v_fmac_f32_e32 v73, v66, v66
	v_add_f32_e32 v84, v85, v84
	v_add_f32_e32 v72, v73, v72
	v_cvt_pk_bf16_f32 v79, v74, v75
	v_add_f32_e32 v74, v84, v72
	ds_bpermute_b32 v75, v156, v74
	v_or_b32_e32 v80, 48, v146
	v_ashrrev_i32_e32 v81, 31, v80
	v_lshlrev_b64 v[82:83], 11, v[80:81]
	v_lshl_add_u64 v[72:73], s[8:9], 0, v[82:83]
	v_lshl_add_u64 v[82:83], v[144:145], 0, v[72:73]
	v_cvt_pk_bf16_f32 v72, v68, v69
	s_waitcnt lgkmcnt(0)
	v_add_f32_e32 v68, v74, v75
	ds_bpermute_b32 v69, v155, v68
	v_cvt_pk_bf16_f32 v73, v70, v71
	v_cvt_pk_bf16_f32 v74, v64, v65
	v_cvt_pk_bf16_f32 v75, v66, v67
	global_store_dwordx4 v[82:83], v[76:79], off sc1
	global_store_dwordx4 v[82:83], v[72:75], off offset:1024 sc1
	s_and_saveexec_b64 s[30:31], s[4:5]
	s_cbranch_execz .LBB0_737
	v_lshlrev_b64 v[64:65], 6, v[80:81]
	v_lshl_add_u64 v[64:65], s[10:11], 0, v[64:65]
	v_lshl_add_u64 v[64:65], s[28:29], 2, v[64:65]
	s_lshl_b32 s12, s43, 2
	s_waitcnt lgkmcnt(0)
	v_add_f32_e32 v66, v68, v69
	v_lshl_add_u64 v[64:65], v[64:65], 0, s[12:13]
	global_store_dword v[64:65], v66, off
.LBB0_737:
	s_or_b64 exec, exec, s[30:31]
	v_mul_f32_e32 v68, v61, v61
	s_waitcnt lgkmcnt(0)
	v_mul_f32_e32 v69, v63, v63
	v_fmac_f32_e32 v68, v60, v60
	v_fmac_f32_e32 v69, v62, v62
	v_add_f32_e32 v68, v68, v69
	v_mul_f32_e32 v69, v57, v57
	v_fmac_f32_e32 v69, v56, v56
	v_cvt_pk_bf16_f32 v60, v60, v61
	v_cvt_pk_bf16_f32 v61, v62, v63
	v_cvt_pk_bf16_f32 v62, v56, v57
	v_mul_f32_e32 v56, v53, v53
	v_mul_f32_e32 v57, v55, v55
	v_fmac_f32_e32 v56, v52, v52
	v_fmac_f32_e32 v57, v54, v54
	v_add_f32_e32 v56, v56, v57
	v_mul_f32_e32 v57, v49, v49
	v_fmac_f32_e32 v57, v48, v48
	v_add_f32_e32 v68, v68, v69
	v_mul_f32_e32 v69, v59, v59
	v_add_f32_e32 v56, v56, v57
	v_mul_f32_e32 v57, v51, v51
	v_fmac_f32_e32 v69, v58, v58
	v_fmac_f32_e32 v57, v50, v50
	v_add_f32_e32 v68, v69, v68
	v_add_f32_e32 v56, v57, v56
	v_cvt_pk_bf16_f32 v63, v58, v59
	v_add_f32_e32 v58, v68, v56
	ds_bpermute_b32 v59, v156, v58
	v_add_u32_e32 v64, 0x80, v146
	v_ashrrev_i32_e32 v65, 31, v64
	v_lshlrev_b64 v[66:67], 11, v[64:65]
	v_lshl_add_u64 v[56:57], s[8:9], 0, v[66:67]
	v_lshl_add_u64 v[66:67], v[144:145], 0, v[56:57]
	v_cvt_pk_bf16_f32 v56, v52, v53
	s_waitcnt lgkmcnt(0)
	v_add_f32_e32 v52, v58, v59
	ds_bpermute_b32 v53, v155, v52
	v_cvt_pk_bf16_f32 v57, v54, v55
	v_cvt_pk_bf16_f32 v58, v48, v49
	v_cvt_pk_bf16_f32 v59, v50, v51
	global_store_dwordx4 v[66:67], v[60:63], off sc1
	global_store_dwordx4 v[66:67], v[56:59], off offset:1024 sc1
	s_and_saveexec_b64 s[30:31], s[4:5]
	s_cbranch_execz .LBB0_739
	v_lshlrev_b64 v[48:49], 6, v[64:65]
	v_lshl_add_u64 v[48:49], s[10:11], 0, v[48:49]
	v_lshl_add_u64 v[48:49], s[28:29], 2, v[48:49]
	s_lshl_b32 s12, s43, 2
	s_waitcnt lgkmcnt(0)
	v_add_f32_e32 v50, v52, v53
	v_lshl_add_u64 v[48:49], v[48:49], 0, s[12:13]
	global_store_dword v[48:49], v50, off
.LBB0_739:
	s_or_b64 exec, exec, s[30:31]
	v_mul_f32_e32 v52, v45, v45
	s_waitcnt lgkmcnt(0)
	v_mul_f32_e32 v53, v47, v47
	v_fmac_f32_e32 v52, v44, v44
	v_fmac_f32_e32 v53, v46, v46
	v_add_f32_e32 v52, v52, v53
	v_mul_f32_e32 v53, v41, v41
	v_fmac_f32_e32 v53, v40, v40
	v_cvt_pk_bf16_f32 v44, v44, v45
	v_cvt_pk_bf16_f32 v45, v46, v47
	v_cvt_pk_bf16_f32 v46, v40, v41
	v_mul_f32_e32 v40, v37, v37
	v_mul_f32_e32 v41, v39, v39
	v_fmac_f32_e32 v40, v36, v36
	v_fmac_f32_e32 v41, v38, v38
	v_add_f32_e32 v40, v40, v41
	v_mul_f32_e32 v41, v33, v33
	v_fmac_f32_e32 v41, v32, v32
	v_add_f32_e32 v52, v52, v53
	v_mul_f32_e32 v53, v43, v43
	v_add_f32_e32 v40, v40, v41
	v_mul_f32_e32 v41, v35, v35
	v_fmac_f32_e32 v53, v42, v42
	v_fmac_f32_e32 v41, v34, v34
	v_add_f32_e32 v52, v53, v52
	v_add_f32_e32 v40, v41, v40
	v_cvt_pk_bf16_f32 v47, v42, v43
	v_add_f32_e32 v42, v52, v40
	ds_bpermute_b32 v43, v156, v42
	v_add_u32_e32 v48, 0x90, v146
	v_ashrrev_i32_e32 v49, 31, v48
	v_lshlrev_b64 v[50:51], 11, v[48:49]
	v_lshl_add_u64 v[40:41], s[8:9], 0, v[50:51]
	v_lshl_add_u64 v[50:51], v[144:145], 0, v[40:41]
	v_cvt_pk_bf16_f32 v40, v36, v37
	s_waitcnt lgkmcnt(0)
	v_add_f32_e32 v36, v42, v43
	ds_bpermute_b32 v37, v155, v36
	v_cvt_pk_bf16_f32 v41, v38, v39
	v_cvt_pk_bf16_f32 v42, v32, v33
	v_cvt_pk_bf16_f32 v43, v34, v35
	global_store_dwordx4 v[50:51], v[44:47], off sc1
	global_store_dwordx4 v[50:51], v[40:43], off offset:1024 sc1
	s_and_saveexec_b64 s[30:31], s[4:5]
	s_cbranch_execz .LBB0_741
	v_lshlrev_b64 v[32:33], 6, v[48:49]
	v_lshl_add_u64 v[32:33], s[10:11], 0, v[32:33]
	v_lshl_add_u64 v[32:33], s[28:29], 2, v[32:33]
	s_lshl_b32 s12, s43, 2
	s_waitcnt lgkmcnt(0)
	v_add_f32_e32 v34, v36, v37
	v_lshl_add_u64 v[32:33], v[32:33], 0, s[12:13]
	global_store_dword v[32:33], v34, off
.LBB0_741:
	s_or_b64 exec, exec, s[30:31]
	v_mul_f32_e32 v36, v29, v29
	s_waitcnt lgkmcnt(0)
	v_mul_f32_e32 v37, v31, v31
	v_fmac_f32_e32 v36, v28, v28
	v_fmac_f32_e32 v37, v30, v30
	v_add_f32_e32 v36, v36, v37
	v_mul_f32_e32 v37, v25, v25
	v_fmac_f32_e32 v37, v24, v24
	v_cvt_pk_bf16_f32 v28, v28, v29
	v_cvt_pk_bf16_f32 v29, v30, v31
	v_cvt_pk_bf16_f32 v30, v24, v25
	v_mul_f32_e32 v24, v21, v21
	v_mul_f32_e32 v25, v23, v23
	v_fmac_f32_e32 v24, v20, v20
	v_fmac_f32_e32 v25, v22, v22
	v_add_f32_e32 v24, v24, v25
	v_mul_f32_e32 v25, v17, v17
	v_fmac_f32_e32 v25, v16, v16
	v_add_f32_e32 v36, v36, v37
	v_mul_f32_e32 v37, v27, v27
	v_add_f32_e32 v24, v24, v25
	v_mul_f32_e32 v25, v19, v19
	v_fmac_f32_e32 v37, v26, v26
	v_fmac_f32_e32 v25, v18, v18
	v_add_f32_e32 v36, v37, v36
	v_add_f32_e32 v24, v25, v24
	v_cvt_pk_bf16_f32 v31, v26, v27
	v_add_f32_e32 v26, v36, v24
	ds_bpermute_b32 v27, v156, v26
	v_add_u32_e32 v32, 0xa0, v146
	v_ashrrev_i32_e32 v33, 31, v32
	v_lshlrev_b64 v[34:35], 11, v[32:33]
	v_lshl_add_u64 v[24:25], s[8:9], 0, v[34:35]
	v_lshl_add_u64 v[34:35], v[144:145], 0, v[24:25]
	v_cvt_pk_bf16_f32 v24, v20, v21
	s_waitcnt lgkmcnt(0)
	v_add_f32_e32 v20, v26, v27
	ds_bpermute_b32 v21, v155, v20
	v_cvt_pk_bf16_f32 v25, v22, v23
	v_cvt_pk_bf16_f32 v26, v16, v17
	v_cvt_pk_bf16_f32 v27, v18, v19
	global_store_dwordx4 v[34:35], v[28:31], off sc1
	global_store_dwordx4 v[34:35], v[24:27], off offset:1024 sc1
	s_and_saveexec_b64 s[30:31], s[4:5]
	s_cbranch_execz .LBB0_743
	v_lshlrev_b64 v[16:17], 6, v[32:33]
	v_lshl_add_u64 v[16:17], s[10:11], 0, v[16:17]
	v_lshl_add_u64 v[16:17], s[28:29], 2, v[16:17]
	s_lshl_b32 s12, s43, 2
	s_waitcnt lgkmcnt(0)
	v_add_f32_e32 v18, v20, v21
	v_lshl_add_u64 v[16:17], v[16:17], 0, s[12:13]
	global_store_dword v[16:17], v18, off
.LBB0_743:
	s_or_b64 exec, exec, s[30:31]
	v_mul_f32_e32 v20, v13, v13
	s_waitcnt lgkmcnt(0)
	v_mul_f32_e32 v21, v15, v15
	v_fmac_f32_e32 v20, v12, v12
	v_fmac_f32_e32 v21, v14, v14
	v_add_f32_e32 v20, v20, v21
	v_mul_f32_e32 v21, v9, v9
	v_fmac_f32_e32 v21, v8, v8
	v_cvt_pk_bf16_f32 v12, v12, v13
	v_cvt_pk_bf16_f32 v13, v14, v15
	v_cvt_pk_bf16_f32 v14, v8, v9
	v_mul_f32_e32 v8, v5, v5
	v_mul_f32_e32 v9, v7, v7
	v_fmac_f32_e32 v8, v4, v4
	v_fmac_f32_e32 v9, v6, v6
	v_add_f32_e32 v8, v8, v9
	v_mul_f32_e32 v9, v1, v1
	v_fmac_f32_e32 v9, v0, v0
	v_add_f32_e32 v20, v20, v21
	v_mul_f32_e32 v21, v11, v11
	v_add_f32_e32 v8, v8, v9
	v_mul_f32_e32 v9, v3, v3
	v_fmac_f32_e32 v21, v10, v10
	v_fmac_f32_e32 v9, v2, v2
	v_add_f32_e32 v20, v21, v20
	v_add_f32_e32 v8, v9, v8
	v_cvt_pk_bf16_f32 v15, v10, v11
	v_add_f32_e32 v10, v20, v8
	ds_bpermute_b32 v11, v156, v10
	v_add_u32_e32 v16, 0xb0, v146
	v_ashrrev_i32_e32 v17, 31, v16
	v_lshlrev_b64 v[18:19], 11, v[16:17]
	v_lshl_add_u64 v[8:9], s[8:9], 0, v[18:19]
	v_lshl_add_u64 v[18:19], v[144:145], 0, v[8:9]
	v_cvt_pk_bf16_f32 v8, v4, v5
	s_waitcnt lgkmcnt(0)
	v_add_f32_e32 v4, v10, v11
	ds_bpermute_b32 v5, v155, v4
	v_cvt_pk_bf16_f32 v9, v6, v7
	v_cvt_pk_bf16_f32 v10, v0, v1
	v_cvt_pk_bf16_f32 v11, v2, v3
	global_store_dwordx4 v[18:19], v[12:15], off sc1
	global_store_dwordx4 v[18:19], v[8:11], off offset:1024 sc1
	s_and_saveexec_b64 s[30:31], s[4:5]
	s_cbranch_execz .LBB0_745
	v_lshlrev_b64 v[0:1], 6, v[16:17]
	v_lshl_add_u64 v[0:1], s[10:11], 0, v[0:1]
	v_lshl_add_u64 v[0:1], s[28:29], 2, v[0:1]
	s_lshl_b32 s12, s43, 2
	s_waitcnt lgkmcnt(0)
	v_add_f32_e32 v2, v4, v5
	v_lshl_add_u64 v[0:1], v[0:1], 0, s[12:13]
	global_store_dword v[0:1], v2, off

.LBB0_803:
	s_cmp_lt_i32 s90, 8
	s_cselect_b64 s[4:5], -1, 0
	s_and_b64 s[0:1], s[4:5], s[6:7]
	s_andn2_b64 vcc, exec, s[0:1]
	s_cbranch_vccnz .LBB0_809
	s_lshl_b32 s0, s2, 3
	s_add_i32 s6, s94, s0
	s_cmpk_gt_i32 s6, 0x7fff
	s_cbranch_scc1 .LBB0_809
	v_readlane_b32 s12, v254, 3
	s_waitcnt vmcnt(0)
	v_lshlrev_b32_e32 v16, 4, v221
	v_readlane_b32 s16, v254, 7
	v_readlane_b32 s17, v254, 8
	s_nop 4
	global_load_dwordx4 v[0:3], v16, s[16:17] offset:3072
	s_waitcnt lgkmcnt(0)
	global_load_dwordx4 v[4:7], v16, s[16:17] offset:2048
	global_load_dwordx4 v[8:11], v16, s[16:17] offset:1024
	global_load_dwordx4 v[12:15], v16, s[16:17]
	v_and_b32_e32 v16, 3, v220
	v_mov_b32_e32 v21, 0
	v_lshlrev_b32_e32 v16, 4, v16
	v_mov_b32_e32 v17, v21
	v_lshl_add_u64 v[24:25], s[10:11], 0, v[16:17]
	v_mbcnt_lo_u32_b32 v16, -1, 0
	v_mbcnt_hi_u32_b32 v16, -1, v16
	v_and_b32_e32 v18, 64, v16
	v_xor_b32_e32 v17, 1, v16
	v_add_u32_e32 v18, 64, v18
	v_cmp_lt_i32_e32 vcc, v17, v18
	v_lshlrev_b32_e32 v20, 3, v221
	v_lshl_add_u64 v[22:23], s[66:67], 0, v[20:21]
	v_cndmask_b32_e32 v17, v16, v17, vcc
	v_bfe_u32 v26, v221, 4, 1
	v_lshlrev_b32_e32 v26, 13, v26
	v_lshrrev_b32_e32 v27, 5, v221
	v_lshl_or_b32 v26, v27, 10, v26
	v_and_b32_e32 v27, 15, v221
	v_lshl_or_b32 v26, v27, 3, v26
	v_add_u32_e32 v26, 0x1000, v26
	v_mov_b32_e32 v27, 0
	v_lshl_add_u64 v[26:27], s[8:9], 0, v[26:27]
	v_lshlrev_b32_e32 v20, 2, v17
	v_xor_b32_e32 v17, 2, v16
	v_cmp_lt_i32_e32 vcc, v17, v18
	v_readlane_b32 s18, v254, 9
	v_readlane_b32 s19, v254, 10
	v_cndmask_b32_e32 v17, v16, v17, vcc
	v_lshlrev_b32_e32 v48, 2, v17
	v_xor_b32_e32 v17, 4, v16
	v_cmp_lt_i32_e32 vcc, v17, v18
	s_lshl_b32 s3, s92, 3
	s_lshl_b32 s18, s92, 4
	v_cndmask_b32_e32 v17, v16, v17, vcc
	v_lshlrev_b32_e32 v49, 2, v17
	v_xor_b32_e32 v17, 8, v16
	v_cmp_lt_i32_e32 vcc, v17, v18
	v_mov_b32_e32 v53, 0x358637bd
	s_mov_b32 s19, 0xf800000
	v_cndmask_b32_e32 v17, v16, v17, vcc
	v_lshlrev_b32_e32 v50, 2, v17
	v_xor_b32_e32 v17, 16, v16
	v_cmp_lt_i32_e32 vcc, v17, v18
	v_mov_b32_e32 v54, 0x260
	v_readlane_b32 s13, v254, 4
	v_cndmask_b32_e32 v17, v16, v17, vcc
	v_lshlrev_b32_e32 v51, 2, v17
	v_xor_b32_e32 v17, 32, v16
	v_cmp_lt_i32_e32 vcc, v17, v18
	v_readlane_b32 s14, v254, 5
	v_readlane_b32 s15, v254, 6
	v_cndmask_b32_e32 v16, v16, v17, vcc
	v_lshlrev_b32_e32 v52, 2, v16
	v_readlane_b32 s20, v254, 11
	v_readlane_b32 s21, v254, 12
	v_readlane_b32 s22, v254, 13
	v_readlane_b32 s23, v254, 14
	v_readlane_b32 s24, v254, 15
	v_readlane_b32 s25, v254, 16
	v_readlane_b32 s26, v254, 17
	v_readlane_b32 s27, v254, 18
	s_branch .LBB0_807

.LBB0_807:
	s_ashr_i32 s7, s6, 31
	s_lshl_b64 s[0:1], s[6:7], 6
	s_waitcnt lgkmcnt(0)
	v_lshl_add_u64 v[16:17], v[24:25], 0, s[0:1]
	global_load_dwordx4 v[30:33], v[16:17], off
	s_add_i32 s12, s3, s6
	s_cmp_lt_i32 s12, 0x8000
	s_cselect_b32 s0, s12, s6
	s_ashr_i32 s1, s0, 31
	s_lshl_b64 s[20:21], s[0:1], 6
	s_lshl_b64 s[14:15], s[0:1], 11
	s_lshr_b32 s100, s0, 3
	s_lshl_b32 s100, s100, 14
	s_and_b32 s101, s0, 7
	s_lshl_b32 s101, s101, 7
	s_add_u32 s100, s100, s101
	s_mov_b32 s101, 0
	s_lshr_b32 s98, s6, 3
	s_lshl_b32 s98, s98, 14
	s_and_b32 s99, s6, 7
	s_lshl_b32 s99, s99, 7
	s_add_u32 s98, s98, s99
	s_mov_b32 s99, 0
	s_lshl_b64 s[0:1], s[0:1], 2
	s_add_u32 s16, s30, s0
	s_addc_u32 s17, s31, s1
	s_lshl_b64 s[0:1], s[6:7], 11
	v_lshl_add_u64 v[28:29], v[22:23], 0, s[0:1]
	global_load_dwordx2 v[34:35], v[28:29], off offset:1536
	v_lshl_add_u64 v[16:17], v[26:27], 0, s[98:99]
	s_lshl_b64 s[0:1], s[6:7], 2
	s_add_u32 s0, s30, s0
	s_addc_u32 s1, s31, s1
	global_load_dwordx2 v[36:37], v[16:17], off offset:-2048
	global_load_dwordx2 v[38:39], v[28:29], off offset:512
	global_load_dwordx2 v[40:41], v[16:17], off
	global_load_dwordx2 v[42:43], v[28:29], off offset:1024
	global_load_dwordx2 v[44:45], v[16:17], off offset:2048
	global_load_dwordx2 v[46:47], v[28:29], off
	global_load_dwordx2 v[56:57], v[16:17], off offset:-4096
	global_load_dword v58, v21, s[0:1]
	v_lshl_add_u64 v[16:17], v[24:25], 0, s[20:21]
	global_load_dwordx4 v[16:19], v[16:17], off
	s_cmpk_gt_i32 s12, 0x7fff
	s_waitcnt vmcnt(10)
	v_mov_b32_e32 v60, v31
	v_mov_b32_e32 v61, v32
	v_mov_b32_e32 v31, v33
	v_pk_add_f32 v[30:31], v[60:61], v[30:31]
	s_waitcnt vmcnt(8)
	v_and_b32_e32 v61, 0xffff0000, v36
	v_add_f32_e32 v30, v30, v31
	ds_bpermute_b32 v32, v20, v30
	v_and_b32_e32 v55, 0xffff0000, v35
	v_lshlrev_b32_e32 v59, 16, v35
	s_waitcnt vmcnt(4)
	v_lshlrev_b32_e32 v70, 16, v44
	v_and_b32_e32 v72, 0xffff0000, v44
	s_waitcnt lgkmcnt(0)
	v_add_f32_e32 v30, v30, v32
	ds_bpermute_b32 v32, v48, v30
	v_lshlrev_b32_e32 v74, 16, v45
	v_and_b32_e32 v76, 0xffff0000, v45
	s_waitcnt vmcnt(2)
	v_lshlrev_b32_e32 v44, 16, v57
	v_and_b32_e32 v45, 0xffff0000, v57
	s_waitcnt lgkmcnt(0)
	v_add_f32_e32 v30, v30, v32
	v_fmamk_f32 v30, v30, 0x3a800000, v53
	v_mul_f32_e32 v32, 0x4f800000, v30
	v_cmp_gt_f32_e32 vcc, s19, v30
	s_waitcnt vmcnt(1)
	v_mul_f32_e32 v57, v58, v55
	v_and_b32_e32 v31, 0xffff0000, v34
	v_cndmask_b32_e32 v30, v30, v32, vcc
	v_sqrt_f32_e32 v32, v30
	v_lshlrev_b32_e32 v33, 16, v34
	v_lshlrev_b32_e32 v35, 16, v36
	v_lshlrev_b32_e32 v34, 16, v38
	v_add_u32_e32 v55, -1, v32
	v_and_b32_e32 v60, 0xffff0000, v38
	v_lshlrev_b32_e32 v62, 16, v39
	v_and_b32_e32 v36, 0xffff0000, v39
	v_lshlrev_b32_e32 v39, 16, v40
	v_lshlrev_b32_e32 v38, 16, v42
	v_and_b32_e32 v65, 0xffff0000, v40
	v_and_b32_e32 v64, 0xffff0000, v42
	v_lshlrev_b32_e32 v66, 16, v43
	v_and_b32_e32 v40, 0xffff0000, v43
	v_lshlrev_b32_e32 v42, 16, v47
	v_and_b32_e32 v43, 0xffff0000, v47
	v_lshlrev_b32_e32 v68, 16, v46
	v_and_b32_e32 v69, 0xffff0000, v46
	v_lshlrev_b32_e32 v46, 16, v56
	v_and_b32_e32 v47, 0xffff0000, v56
	v_mul_f32_e32 v71, v58, v59
	v_add_u32_e32 v56, 1, v32
	v_fma_f32 v59, -v55, v32, v30
	v_fma_f32 v73, -v56, v32, v30
	v_cmp_ge_f32_e64 s[0:1], 0, v59
	v_lshlrev_b32_e32 v63, 16, v37
	v_and_b32_e32 v37, 0xffff0000, v37
	v_cndmask_b32_e64 v32, v32, v55, s[0:1]
	v_cmp_lt_f32_e64 s[0:1], 0, v73
	v_lshlrev_b32_e32 v67, 16, v41
	v_and_b32_e32 v41, 0xffff0000, v41
	v_cndmask_b32_e64 v32, v32, v56, s[0:1]
	v_mul_f32_e32 v55, 0x37800000, v32
	v_cndmask_b32_e32 v32, v32, v55, vcc
	v_cmp_class_f32_e32 vcc, v30, v54
	v_mov_b32_e32 v73, v58
	s_waitcnt vmcnt(0)
	v_add_f32_e32 v16, v16, v17
	v_cndmask_b32_e32 v30, v32, v30, vcc
	v_div_scale_f32 v32, s[0:1], v30, v30, 1.0
	v_rcp_f32_e32 v55, v32
	v_div_scale_f32 v56, vcc, 1.0, v30, 1.0
	v_add_f32_e32 v18, v18, v19
	v_fma_f32 v59, -v32, v55, 1.0
	v_fmac_f32_e32 v55, v59, v55
	v_mul_f32_e32 v59, v56, v55
	v_fma_f32 v75, -v32, v59, v56
	v_fmac_f32_e32 v59, v75, v55
	v_fma_f32 v32, -v32, v59, v56
	v_div_fmas_f32 v32, v32, v55, v59
	v_div_fixup_f32 v59, v32, v30, 1.0
	v_mov_b32_e32 v30, v59
	v_mul_f32_e32 v32, v59, v74
	v_pk_mul_f32 v[44:45], v[30:31], v[44:45] op_sel_hi:[0,1]
	v_pk_mul_f32 v[34:35], v[58:59], v[34:35]
	v_pk_mul_f32 v[60:61], v[58:59], v[60:61]
	v_pk_mul_f32 v[62:63], v[58:59], v[62:63]
	v_pk_mul_f32 v[36:37], v[58:59], v[36:37]
	v_pk_mul_f32 v[38:39], v[58:59], v[38:39]
	v_pk_mul_f32 v[64:65], v[58:59], v[64:65]
	v_pk_mul_f32 v[66:67], v[58:59], v[66:67]
	v_pk_mul_f32 v[40:41], v[58:59], v[40:41]
	v_mul_f32_e32 v75, v59, v70
	v_mul_f32_e32 v77, v59, v72
	v_mul_f32_e32 v55, v59, v76
	v_mul_f32_e32 v59, v2, v32
	v_pk_mul_f32 v[46:47], v[30:31], v[46:47] op_sel_hi:[0,1]
	v_pk_mul_f32 v[44:45], v[14:15], v[44:45]
	v_pk_mul_f32 v[46:47], v[12:13], v[46:47]
	v_pk_fma_f32 v[80:81], v[58:59], v[42:43], v[44:45] op_sel_hi:[0,1,1]
	v_pk_fma_f32 v[68:69], v[58:59], v[68:69], v[46:47] op_sel_hi:[0,1,1]
	v_pk_mov_b32 v[42:43], v[80:81], v[0:1] op_sel:[1,0]
	v_mov_b32_e32 v74, v81
	v_pk_mul_f32 v[42:43], v[42:43], v[74:75]
	v_pk_mov_b32 v[82:83], v[68:69], v[0:1] op_sel:[1,0]
	v_mov_b32_e32 v74, v69
	v_mov_b32_e32 v72, v80
	v_mov_b32_e32 v32, v80
	v_mov_b32_e32 v44, v68
	v_mov_b32_e32 v45, v58
	v_mov_b32_e32 v46, v68
	v_mov_b32_e32 v47, v33
	v_pk_mul_f32 v[74:75], v[82:83], v[74:75]
	v_pk_fma_f32 v[32:33], v[72:73], v[32:33], v[42:43]
	v_pk_fma_f32 v[72:73], v[44:45], v[46:47], v[74:75]
	v_mul_f32_e32 v79, v3, v55
	v_pk_add_f32 v[42:43], v[72:73], v[32:33]
	v_pk_mul_f32 v[32:33], v[72:73], v[32:33]
	v_add_f32_e32 v16, v16, v18
	v_mov_b32_e32 v43, v33
	v_mov_b32_e32 v32, v63
	v_mov_b32_e32 v33, v37
	v_mov_b32_e32 v63, v36
	v_mov_b32_e32 v36, v35
	v_mov_b32_e32 v37, v61
	v_mov_b32_e32 v35, v60
	v_pk_fma_f32 v[60:61], v[8:9], v[36:37], v[34:35]
	v_pk_fma_f32 v[62:63], v[10:11], v[32:33], v[62:63]
	v_mov_b32_e32 v36, v61
	v_mov_b32_e32 v37, v1
	v_mov_b32_e32 v76, v61
	v_mov_b32_e32 v32, v63
	v_mov_b32_e32 v33, v1
	v_mov_b32_e32 v34, v60
	v_mov_b32_e32 v35, v58
	v_mov_b32_e32 v30, v60
	v_pk_mul_f32 v[36:37], v[36:37], v[76:77]
	v_mov_b32_e32 v76, v63
	v_pk_fma_f32 v[74:75], v[34:35], v[30:31], v[36:37]
	v_mov_b32_e32 v34, v62
	v_mov_b32_e32 v30, v62
	v_pk_mul_f32 v[32:33], v[32:33], v[76:77]
	ds_bpermute_b32 v18, v20, v16
	v_pk_fma_f32 v[30:31], v[34:35], v[30:31], v[32:33]
	s_waitcnt lgkmcnt(0)
	v_add_f32_e32 v16, v16, v18
	v_pk_add_f32 v[32:33], v[74:75], v[30:31]
	v_pk_mul_f32 v[30:31], v[74:75], v[30:31]
	v_mov_b32_e32 v74, v73
	v_mov_b32_e32 v33, v31
	v_pk_add_f32 v[30:31], v[42:43], v[32:33]
	v_mov_b32_e32 v32, v67
	v_mov_b32_e32 v33, v41
	v_mov_b32_e32 v67, v40
	v_pk_fma_f32 v[66:67], v[6:7], v[32:33], v[66:67]
	s_nop 0
	v_mov_b32_e32 v78, v66
	v_mov_b32_e32 v56, v66
	v_pk_add_f32 v[56:57], v[78:79], v[56:57]
	v_mul_f32_e32 v32, v67, v67
	v_pk_fma_f32 v[32:33], v[66:67], v[66:67], v[32:33] op_sel_hi:[1,1,0]
	v_pk_mul_f32 v[34:35], v[56:57], v[56:57]
	s_nop 0
	v_mov_b32_e32 v33, v35
	v_mov_b32_e32 v34, v39
	v_mov_b32_e32 v35, v65
	v_mov_b32_e32 v39, v64
	v_pk_fma_f32 v[64:65], v[4:5], v[34:35], v[38:39]
	s_nop 0
	v_mov_b32_e32 v58, v64
	v_mov_b32_e32 v70, v64
	v_pk_add_f32 v[58:59], v[58:59], v[70:71]
	v_mul_f32_e32 v34, v65, v65
	v_pk_fma_f32 v[34:35], v[64:65], v[64:65], v[34:35] op_sel_hi:[1,1,0]
	v_pk_mul_f32 v[36:37], v[58:59], v[58:59]
	v_lshl_add_u64 v[70:71], v[26:27], 0, s[100:101]
	v_mov_b32_e32 v35, v37
	v_pk_add_f32 v[32:33], v[34:35], v[32:33]
	v_lshl_add_u64 v[34:35], v[22:23], 0, s[14:15]
	v_pk_add_f32 v[30:31], v[30:31], v[32:33]
	s_nop 0
	v_add_f32_e32 v31, v30, v31
	ds_bpermute_b32 v32, v20, v31
	global_load_dword v30, v21, s[16:17]
	s_waitcnt lgkmcnt(0)
	v_add_f32_e32 v31, v31, v32
	ds_bpermute_b32 v36, v48, v31
	global_load_dwordx2 v[32:33], v[34:35], off
	global_load_dwordx2 v[42:43], v[34:35], off offset:512
	global_load_dwordx2 v[38:39], v[34:35], off offset:1024
	global_load_dwordx2 v[46:47], v[34:35], off offset:1536
	s_waitcnt lgkmcnt(0)
	v_add_f32_e32 v31, v31, v36
	global_load_dwordx2 v[34:35], v[70:71], off offset:-4096
	global_load_dwordx2 v[44:45], v[70:71], off offset:-2048
	global_load_dwordx2 v[40:41], v[70:71], off
	global_load_dwordx2 v[36:37], v[70:71], off offset:2048
	ds_bpermute_b32 v55, v49, v31
	s_waitcnt lgkmcnt(0)
	v_add_f32_e32 v31, v31, v55
	ds_bpermute_b32 v55, v50, v31
	s_waitcnt lgkmcnt(0)
	v_add_f32_e32 v31, v31, v55
	ds_bpermute_b32 v55, v51, v31
	s_waitcnt lgkmcnt(0)
	v_add_f32_e32 v31, v31, v55
	ds_bpermute_b32 v55, v52, v31
	s_waitcnt lgkmcnt(0)
	v_add_f32_e32 v17, v31, v55
	v_fmamk_f32 v17, v17, 0x3a800000, v53
	v_mul_f32_e32 v31, 0x4f800000, v17
	v_cmp_gt_f32_e32 vcc, s19, v17
	s_nop 1
	v_cndmask_b32_e32 v17, v17, v31, vcc
	v_sqrt_f32_e32 v31, v17
	s_nop 0
	v_add_u32_e32 v19, -1, v31
	v_fma_f32 v55, -v19, v31, v17
	v_cmp_ge_f32_e64 s[0:1], 0, v55
	v_add_u32_e32 v55, 1, v31
	s_nop 0
	v_cndmask_b32_e64 v19, v31, v19, s[0:1]
	v_fma_f32 v31, -v55, v31, v17
	v_cmp_lt_f32_e64 s[0:1], 0, v31
	s_nop 1
	v_cndmask_b32_e64 v19, v19, v55, s[0:1]
	v_mul_f32_e32 v31, 0x37800000, v19
	v_cndmask_b32_e32 v19, v19, v31, vcc
	v_cmp_class_f32_e32 vcc, v17, v54
	s_nop 1
	v_cndmask_b32_e32 v19, v19, v17, vcc
	v_div_scale_f32 v31, s[0:1], v19, v19, 1.0
	v_rcp_f32_e32 v55, v31
	ds_bpermute_b32 v17, v48, v16
	v_fma_f32 v18, -v31, v55, 1.0
	v_fmac_f32_e32 v55, v18, v55
	v_div_scale_f32 v18, vcc, 1.0, v19, 1.0
	v_mul_f32_e32 v56, v18, v55
	v_fma_f32 v58, -v31, v56, v18
	v_fmac_f32_e32 v56, v58, v55
	v_fma_f32 v18, -v31, v56, v18
	v_div_fmas_f32 v18, v18, v55, v56
	v_div_fixup_f32 v18, v18, v19, 1.0
	v_pk_mul_f32 v[60:61], v[18:19], v[60:61] op_sel_hi:[0,1]
	v_pk_mul_f32 v[62:63], v[18:19], v[62:63] op_sel_hi:[0,1]
	v_cvt_pk_bf16_f32 v60, v60, v61
	v_cvt_pk_bf16_f32 v61, v62, v63
	global_store_dwordx2 v[28:29], v[60:61], off offset:512 sc1
	v_pk_mul_f32 v[60:61], v[18:19], v[64:65] op_sel_hi:[0,1]
	v_pk_mul_f32 v[62:63], v[18:19], v[66:67] op_sel_hi:[0,1]
	v_cvt_pk_bf16_f32 v60, v60, v61
	v_cvt_pk_bf16_f32 v61, v62, v63
	v_mov_b32_e32 v56, v59
	v_pk_mul_f32 v[68:69], v[18:19], v[68:69] op_sel_hi:[0,1]
	v_pk_mul_f32 v[70:71], v[18:19], v[80:81] op_sel_hi:[0,1]
	global_store_dwordx2 v[28:29], v[60:61], off offset:1024 sc1
	v_pk_mul_f32 v[60:61], v[18:19], v[74:75] op_sel_hi:[0,1]
	v_pk_mul_f32 v[18:19], v[18:19], v[56:57] op_sel_hi:[0,1]
	v_cvt_pk_bf16_f32 v68, v68, v69
	v_cvt_pk_bf16_f32 v69, v70, v71
	v_cvt_pk_bf16_f32 v58, v60, v61
	v_cvt_pk_bf16_f32 v59, v18, v19
	global_store_dwordx2 v[28:29], v[68:69], off sc1
	global_store_dwordx2 v[28:29], v[58:59], off offset:1536 sc1
	s_cbranch_scc1 .LBB0_806
	s_waitcnt lgkmcnt(0)
	v_add_f32_e32 v16, v16, v17
	v_fmamk_f32 v16, v16, 0x3a800000, v53
	v_mul_f32_e32 v17, 0x4f800000, v16
	v_cmp_gt_f32_e32 vcc, s19, v16
	s_waitcnt vmcnt(8)
	v_lshlrev_b32_e32 v19, 16, v47
	s_waitcnt vmcnt(6)
	v_lshlrev_b32_e32 v57, 16, v44
	v_cndmask_b32_e32 v16, v16, v17, vcc
	v_sqrt_f32_e32 v18, v16
	v_and_b32_e32 v17, 0xffff0000, v47
	v_lshlrev_b32_e32 v47, 16, v46
	v_and_b32_e32 v59, 0xffff0000, v44
	v_add_u32_e32 v28, -1, v18
	v_fma_f32 v29, -v28, v18, v16
	v_cmp_ge_f32_e64 s[0:1], 0, v29
	v_add_u32_e32 v29, 1, v18
	v_lshlrev_b32_e32 v61, 16, v45
	v_cndmask_b32_e64 v28, v18, v28, s[0:1]
	v_fma_f32 v18, -v29, v18, v16
	v_cmp_lt_f32_e64 s[0:1], 0, v18
	v_and_b32_e32 v45, 0xffff0000, v45
	v_and_b32_e32 v44, 0xffff0000, v43
	v_cndmask_b32_e64 v18, v28, v29, s[0:1]
	v_mul_f32_e32 v28, 0x37800000, v18
	v_cndmask_b32_e32 v18, v18, v28, vcc
	v_cmp_class_f32_e32 vcc, v16, v54
	v_and_b32_e32 v29, 0xffff0000, v46
	v_lshlrev_b32_e32 v56, 16, v42
	v_cndmask_b32_e32 v16, v18, v16, vcc
	v_div_scale_f32 v18, s[0:1], v16, v16, 1.0
	v_rcp_f32_e32 v28, v18
	v_and_b32_e32 v58, 0xffff0000, v42
	v_lshlrev_b32_e32 v60, 16, v43
	s_waitcnt vmcnt(5)
	v_and_b32_e32 v63, 0xffff0000, v40
	v_fma_f32 v31, -v18, v28, 1.0
	v_fmac_f32_e32 v28, v31, v28
	v_div_scale_f32 v31, vcc, 1.0, v16, 1.0
	v_mul_f32_e32 v46, v31, v28
	v_fma_f32 v55, -v18, v46, v31
	v_fmac_f32_e32 v46, v55, v28
	v_fma_f32 v18, -v18, v46, v31
	v_div_fmas_f32 v18, v18, v28, v46
	v_div_fixup_f32 v31, v18, v16, 1.0
	v_pk_mul_f32 v[42:43], v[30:31], v[44:45]
	v_lshlrev_b32_e32 v45, 16, v40
	v_lshlrev_b32_e32 v65, 16, v41
	v_and_b32_e32 v41, 0xffff0000, v41
	v_and_b32_e32 v40, 0xffff0000, v39
	s_waitcnt vmcnt(4)
	v_lshlrev_b32_e32 v16, 16, v36
	v_lshlrev_b32_e32 v44, 16, v38
	v_and_b32_e32 v62, 0xffff0000, v38
	v_lshlrev_b32_e32 v64, 16, v39
	v_pk_mul_f32 v[38:39], v[30:31], v[40:41]
	v_mul_f32_e32 v41, v31, v16
	v_and_b32_e32 v16, 0xffff0000, v36
	v_mul_f32_e32 v67, v31, v16
	v_lshlrev_b32_e32 v16, 16, v37
	v_mul_f32_e32 v16, v31, v16
	v_mul_f32_e32 v69, v2, v16
	v_and_b32_e32 v16, 0xffff0000, v37
	v_mul_f32_e32 v16, v31, v16
	v_mul_f32_e32 v17, v30, v17
	v_mul_f32_e32 v37, v3, v16
	v_lshlrev_b32_e32 v72, 16, v35
	v_and_b32_e32 v73, 0xffff0000, v35
	v_mov_b32_e32 v16, v31
	v_pk_mul_f32 v[72:73], v[16:17], v[72:73] op_sel_hi:[0,1]
	v_lshlrev_b32_e32 v70, 16, v33
	v_and_b32_e32 v71, 0xffff0000, v33
	v_pk_mul_f32 v[72:73], v[14:15], v[72:73]
	v_and_b32_e32 v33, 0xffff0000, v34
	v_pk_fma_f32 v[70:71], v[30:31], v[70:71], v[72:73] op_sel_hi:[0,1,1]
	v_lshlrev_b32_e32 v72, 16, v32
	v_and_b32_e32 v73, 0xffff0000, v32
	v_lshlrev_b32_e32 v32, 16, v34
	v_pk_mul_f32 v[32:33], v[16:17], v[32:33] op_sel_hi:[0,1]
	v_pk_mul_f32 v[32:33], v[12:13], v[32:33]
	v_mov_b32_e32 v40, v71
	v_pk_fma_f32 v[32:33], v[30:31], v[72:73], v[32:33] op_sel_hi:[0,1,1]
	v_pk_mov_b32 v[72:73], v[70:71], v[0:1] op_sel:[1,0]
	v_pk_mov_b32 v[78:79], v[32:33], v[0:1] op_sel:[1,0]
	v_pk_mul_f32 v[72:73], v[72:73], v[40:41]
	v_mov_b32_e32 v40, v33
	v_mov_b32_e32 v34, v70
	v_mov_b32_e32 v35, v30
	v_mov_b32_e32 v46, v70
	v_mov_b32_e32 v74, v32
	v_mov_b32_e32 v75, v30
	v_mov_b32_e32 v76, v32
	v_mov_b32_e32 v77, v47
	v_pk_mul_f32 v[40:41], v[78:79], v[40:41]
	v_pk_fma_f32 v[34:35], v[34:35], v[46:47], v[72:73]
	v_pk_fma_f32 v[40:41], v[74:75], v[76:77], v[40:41]
	v_pk_mul_f32 v[60:61], v[30:31], v[60:61]
	v_pk_add_f32 v[46:47], v[40:41], v[34:35]
	v_pk_mul_f32 v[34:35], v[40:41], v[34:35]
	v_pk_mul_f32 v[56:57], v[30:31], v[56:57]
	v_pk_mul_f32 v[58:59], v[30:31], v[58:59]
	v_mov_b32_e32 v47, v35
	v_mov_b32_e32 v34, v61
	v_mov_b32_e32 v35, v43
	v_mov_b32_e32 v61, v42
	v_pk_fma_f32 v[34:35], v[10:11], v[34:35], v[60:61]
	v_mov_b32_e32 v60, v57
	v_mov_b32_e32 v61, v59
	v_mov_b32_e32 v57, v58
	v_pk_fma_f32 v[56:57], v[8:9], v[60:61], v[56:57]
	v_mov_b32_e32 v61, v1
	v_mov_b32_e32 v60, v57
	v_mov_b32_e32 v66, v57
	v_mov_b32_e32 v42, v35
	v_mov_b32_e32 v43, v1
	v_mov_b32_e32 v58, v56
	v_mov_b32_e32 v59, v30
	v_mov_b32_e32 v28, v56
	v_pk_mul_f32 v[60:61], v[60:61], v[66:67]
	v_mov_b32_e32 v66, v35
	v_mul_f32_e32 v19, v30, v19
	v_pk_mul_f32 v[44:45], v[30:31], v[44:45]
	v_pk_mul_f32 v[62:63], v[30:31], v[62:63]
	v_pk_mul_f32 v[64:65], v[30:31], v[64:65]
	v_pk_fma_f32 v[58:59], v[58:59], v[28:29], v[60:61]
	v_mov_b32_e32 v60, v34
	v_mov_b32_e32 v61, v30
	v_mov_b32_e32 v28, v34
	v_pk_mul_f32 v[30:31], v[42:43], v[66:67]
	s_ashr_i32 s13, s12, 31
	v_pk_fma_f32 v[28:29], v[60:61], v[28:29], v[30:31]
	s_nop 0
	v_pk_add_f32 v[30:31], v[58:59], v[28:29]
	v_pk_mul_f32 v[28:29], v[58:59], v[28:29]
	v_mov_b32_e32 v58, v41
	v_mov_b32_e32 v31, v29
	v_pk_add_f32 v[28:29], v[46:47], v[30:31]
	v_mov_b32_e32 v30, v65
	v_mov_b32_e32 v31, v39
	v_mov_b32_e32 v65, v38
	v_pk_fma_f32 v[30:31], v[6:7], v[30:31], v[64:65]
	s_nop 0
	v_mov_b32_e32 v36, v30
	v_mov_b32_e32 v16, v30
	v_pk_add_f32 v[16:17], v[36:37], v[16:17]
	v_mul_f32_e32 v18, v31, v31
	v_pk_fma_f32 v[36:37], v[30:31], v[30:31], v[18:19] op_sel_hi:[1,1,0]
	v_pk_mul_f32 v[38:39], v[16:17], v[16:17]
	s_nop 0
	v_mov_b32_e32 v37, v39
	v_mov_b32_e32 v38, v45
	v_mov_b32_e32 v39, v63
	v_mov_b32_e32 v45, v62
	v_pk_fma_f32 v[38:39], v[4:5], v[38:39], v[44:45]
	s_nop 0
	v_mov_b32_e32 v68, v38
	v_mov_b32_e32 v18, v38
	v_pk_add_f32 v[18:19], v[68:69], v[18:19]
	v_mul_f32_e32 v16, v39, v39
	v_pk_fma_f32 v[42:43], v[38:39], v[38:39], v[16:17] op_sel_hi:[1,1,0]
	v_pk_mul_f32 v[44:45], v[18:19], v[18:19]
	s_nop 0
	v_mov_b32_e32 v43, v45
	v_pk_add_f32 v[36:37], v[42:43], v[36:37]
	s_nop 0
	v_pk_add_f32 v[28:29], v[28:29], v[36:37]
	s_nop 0
	v_add_f32_e32 v16, v28, v29
	ds_bpermute_b32 v18, v20, v16
	s_waitcnt lgkmcnt(0)
	v_add_f32_e32 v16, v16, v18
	ds_bpermute_b32 v18, v48, v16
	s_waitcnt lgkmcnt(0)
	v_add_f32_e32 v16, v16, v18
	ds_bpermute_b32 v18, v49, v16
	s_waitcnt lgkmcnt(0)
	v_add_f32_e32 v16, v16, v18
	ds_bpermute_b32 v18, v50, v16
	s_waitcnt lgkmcnt(0)
	v_add_f32_e32 v16, v16, v18
	ds_bpermute_b32 v18, v51, v16
	s_waitcnt lgkmcnt(0)
	v_add_f32_e32 v16, v16, v18
	ds_bpermute_b32 v18, v52, v16
	s_waitcnt lgkmcnt(0)
	v_add_f32_e32 v16, v16, v18
	v_fmamk_f32 v16, v16, 0x3a800000, v53
	v_mul_f32_e32 v18, 0x4f800000, v16
	v_cmp_gt_f32_e32 vcc, s19, v16
	s_nop 1
	v_cndmask_b32_e32 v16, v16, v18, vcc
	v_sqrt_f32_e32 v18, v16
	s_nop 0
	v_add_u32_e32 v28, -1, v18
	v_fma_f32 v29, -v28, v18, v16
	v_cmp_ge_f32_e64 s[0:1], 0, v29
	v_add_u32_e32 v29, 1, v18
	s_nop 0
	v_cndmask_b32_e64 v28, v18, v28, s[0:1]
	v_fma_f32 v18, -v29, v18, v16
	v_cmp_lt_f32_e64 s[0:1], 0, v18
	s_nop 1
	v_cndmask_b32_e64 v18, v28, v29, s[0:1]
	v_mul_f32_e32 v28, 0x37800000, v18
	v_cndmask_b32_e32 v18, v18, v28, vcc
	v_cmp_class_f32_e32 vcc, v16, v54
	s_nop 1
	v_cndmask_b32_e32 v16, v18, v16, vcc
	v_div_scale_f32 v18, s[0:1], v16, v16, 1.0
	v_rcp_f32_e32 v36, v18
	s_lshl_b64 s[0:1], s[12:13], 11
	v_lshl_add_u64 v[28:29], v[22:23], 0, s[0:1]
	v_fma_f32 v37, -v18, v36, 1.0
	v_fmac_f32_e32 v36, v37, v36
	v_div_scale_f32 v37, vcc, 1.0, v16, 1.0
	v_mul_f32_e32 v40, v37, v36
	v_fma_f32 v42, -v18, v40, v37
	v_fmac_f32_e32 v40, v42, v36
	v_fma_f32 v18, -v18, v40, v37
	v_div_fmas_f32 v18, v18, v36, v40
	v_div_fixup_f32 v18, v18, v16, 1.0
	v_pk_mul_f32 v[32:33], v[18:19], v[32:33] op_sel_hi:[0,1]
	v_pk_mul_f32 v[36:37], v[18:19], v[70:71] op_sel_hi:[0,1]
	v_cvt_pk_bf16_f32 v32, v32, v33
	v_cvt_pk_bf16_f32 v33, v36, v37
	global_store_dwordx2 v[28:29], v[32:33], off sc1
	v_pk_mul_f32 v[32:33], v[18:19], v[56:57] op_sel_hi:[0,1]
	v_pk_mul_f32 v[34:35], v[18:19], v[34:35] op_sel_hi:[0,1]
	v_cvt_pk_bf16_f32 v32, v32, v33
	v_cvt_pk_bf16_f32 v33, v34, v35
	global_store_dwordx2 v[28:29], v[32:33], off offset:512 sc1
	v_pk_mul_f32 v[32:33], v[18:19], v[38:39] op_sel_hi:[0,1]
	v_pk_mul_f32 v[30:31], v[18:19], v[30:31] op_sel_hi:[0,1]
	v_mov_b32_e32 v16, v19
	v_cvt_pk_bf16_f32 v32, v32, v33
	v_cvt_pk_bf16_f32 v33, v30, v31
	v_pk_mul_f32 v[30:31], v[18:19], v[58:59] op_sel_hi:[0,1]
	v_pk_mul_f32 v[16:17], v[18:19], v[16:17] op_sel_hi:[0,1]
	v_cvt_pk_bf16_f32 v30, v30, v31
	v_cvt_pk_bf16_f32 v31, v16, v17
	global_store_dwordx2 v[28:29], v[32:33], off offset:1024 sc1
	global_store_dwordx2 v[28:29], v[30:31], off offset:1536 sc1
	s_branch .LBB0_806

.LBB0_957:
	v_mul_f32_e32 v157, v125, v125
	v_mul_f32_e32 v160, v127, v127
	v_fmac_f32_e32 v157, v124, v124
	v_fmac_f32_e32 v160, v126, v126
	v_add_f32_e32 v157, v157, v160
	v_mul_f32_e32 v160, v121, v121
	v_fmac_f32_e32 v160, v120, v120
	v_cvt_pk_bf16_f32 v124, v124, v125
	v_cvt_pk_bf16_f32 v125, v126, v127
	v_cvt_pk_bf16_f32 v126, v120, v121
	v_mul_f32_e32 v120, v117, v117
	v_mul_f32_e32 v121, v119, v119
	v_fmac_f32_e32 v120, v116, v116
	v_fmac_f32_e32 v121, v118, v118
	v_add_f32_e32 v120, v120, v121
	v_mul_f32_e32 v121, v113, v113
	v_and_b32_e32 v155, 64, v154
	v_fmac_f32_e32 v121, v112, v112
	v_xor_b32_e32 v147, 16, v154
	v_add_u32_e32 v155, 64, v155
	v_add_f32_e32 v157, v157, v160
	v_mul_f32_e32 v160, v123, v123
	v_add_f32_e32 v120, v120, v121
	v_mul_f32_e32 v121, v115, v115
	v_cmp_lt_i32_e32 vcc, v147, v155
	v_fmac_f32_e32 v160, v122, v122
	v_fmac_f32_e32 v121, v114, v114
	v_cndmask_b32_e32 v147, v154, v147, vcc
	v_add_f32_e32 v157, v160, v157
	v_add_f32_e32 v120, v121, v120
	v_lshlrev_b32_e32 v156, 2, v147
	v_xor_b32_e32 v147, 32, v154
	v_cvt_pk_bf16_f32 v127, v122, v123
	v_add_f32_e32 v122, v157, v120
	v_cmp_lt_i32_e32 vcc, v147, v155
	ds_bpermute_b32 v123, v156, v122
	v_lshl_add_u32 v146, s30, 8, v148
	v_cndmask_b32_e32 v147, v154, v147, vcc
	v_lshlrev_b32_e32 v155, 2, v147
	v_ashrrev_i32_e32 v147, 31, v146
	v_and_b32_e32 v214, 0x40, v150
	v_and_b32_e32 v215, 0x38, v150
	v_lshlrev_b32_e32 v214, 7, v214
	v_lshl_or_b32 v214, v215, 1, v214
	v_and_b32_e32 v215, 7, v148
	v_mul_u32_u24_e32 v215, 0x780, v215
	v_sub_u32_e32 v214, v214, v215
	v_lshl_add_u32 v144, s14, 11, v214
	v_lshlrev_b64 v[158:159], 11, v[146:147]
	v_ashrrev_i32_e32 v145, 31, v144
	v_lshl_add_u64 v[120:121], s[66:67], 0, v[158:159]
	v_lshl_add_u64 v[158:159], v[144:145], 0, v[120:121]
	v_cvt_pk_bf16_f32 v120, v116, v117
	s_waitcnt lgkmcnt(0)
	v_add_f32_e32 v116, v122, v123
	ds_bpermute_b32 v117, v155, v116
	s_lshl_b32 s30, s14, 2
	s_ashr_i32 s31, s30, 31
	v_cvt_pk_bf16_f32 v121, v118, v119
	v_cvt_pk_bf16_f32 v122, v112, v113
	v_cvt_pk_bf16_f32 v123, v114, v115
	global_store_dwordx4 v[158:159], v[124:127], off sc1
	global_store_dwordx4 v[158:159], v[120:123], off offset:1024 sc1
	s_and_saveexec_b64 s[34:35], s[4:5]
	s_cbranch_execz .LBB0_959
	v_lshlrev_b64 v[112:113], 6, v[146:147]
	v_lshl_add_u64 v[112:113], s[0:1], 0, v[112:113]
	v_lshl_add_u64 v[112:113], s[30:31], 2, v[112:113]
	s_lshl_b32 s14, s45, 2
	s_waitcnt lgkmcnt(0)
	v_add_f32_e32 v114, v116, v117
	v_lshl_add_u64 v[112:113], v[112:113], 0, s[14:15]
	global_store_dword v[112:113], v114, off
.LBB0_959:
	s_or_b64 exec, exec, s[34:35]
	v_mul_f32_e32 v116, v109, v109
	s_waitcnt lgkmcnt(0)
	v_mul_f32_e32 v117, v111, v111
	v_fmac_f32_e32 v116, v108, v108
	v_fmac_f32_e32 v117, v110, v110
	v_add_f32_e32 v116, v116, v117
	v_mul_f32_e32 v117, v105, v105
	v_fmac_f32_e32 v117, v104, v104
	v_cvt_pk_bf16_f32 v108, v108, v109
	v_cvt_pk_bf16_f32 v109, v110, v111
	v_cvt_pk_bf16_f32 v110, v104, v105
	v_mul_f32_e32 v104, v101, v101
	v_mul_f32_e32 v105, v103, v103
	v_fmac_f32_e32 v104, v100, v100
	v_fmac_f32_e32 v105, v102, v102
	v_add_f32_e32 v104, v104, v105
	v_mul_f32_e32 v105, v97, v97
	v_fmac_f32_e32 v105, v96, v96
	v_add_f32_e32 v116, v116, v117
	v_mul_f32_e32 v117, v107, v107
	v_add_f32_e32 v104, v104, v105
	v_mul_f32_e32 v105, v99, v99
	v_fmac_f32_e32 v117, v106, v106
	v_fmac_f32_e32 v105, v98, v98
	v_add_f32_e32 v116, v117, v116
	v_add_f32_e32 v104, v105, v104
	v_cvt_pk_bf16_f32 v111, v106, v107
	v_add_f32_e32 v106, v116, v104
	ds_bpermute_b32 v107, v156, v106
	v_or_b32_e32 v112, 16, v146
	v_ashrrev_i32_e32 v113, 31, v112
	v_lshlrev_b64 v[114:115], 11, v[112:113]
	v_lshl_add_u64 v[104:105], s[66:67], 0, v[114:115]
	v_lshl_add_u64 v[114:115], v[144:145], 0, v[104:105]
	v_cvt_pk_bf16_f32 v104, v100, v101
	s_waitcnt lgkmcnt(0)
	v_add_f32_e32 v100, v106, v107
	ds_bpermute_b32 v101, v155, v100
	v_cvt_pk_bf16_f32 v105, v102, v103
	v_cvt_pk_bf16_f32 v106, v96, v97
	v_cvt_pk_bf16_f32 v107, v98, v99
	global_store_dwordx4 v[114:115], v[108:111], off sc1
	global_store_dwordx4 v[114:115], v[104:107], off offset:1024 sc1
	s_and_saveexec_b64 s[34:35], s[4:5]
	s_cbranch_execz .LBB0_961
	v_lshlrev_b64 v[96:97], 6, v[112:113]
	v_lshl_add_u64 v[96:97], s[0:1], 0, v[96:97]
	v_lshl_add_u64 v[96:97], s[30:31], 2, v[96:97]
	s_lshl_b32 s14, s45, 2
	s_waitcnt lgkmcnt(0)
	v_add_f32_e32 v98, v100, v101
	v_lshl_add_u64 v[96:97], v[96:97], 0, s[14:15]
	global_store_dword v[96:97], v98, off
.LBB0_961:
	s_or_b64 exec, exec, s[34:35]
	v_mul_f32_e32 v100, v93, v93
	s_waitcnt lgkmcnt(0)
	v_mul_f32_e32 v101, v95, v95
	v_fmac_f32_e32 v100, v92, v92
	v_fmac_f32_e32 v101, v94, v94
	v_add_f32_e32 v100, v100, v101
	v_mul_f32_e32 v101, v89, v89
	v_fmac_f32_e32 v101, v88, v88
	v_cvt_pk_bf16_f32 v92, v92, v93
	v_cvt_pk_bf16_f32 v93, v94, v95
	v_cvt_pk_bf16_f32 v94, v88, v89
	v_mul_f32_e32 v88, v85, v85
	v_mul_f32_e32 v89, v87, v87
	v_fmac_f32_e32 v88, v84, v84
	v_fmac_f32_e32 v89, v86, v86
	v_add_f32_e32 v88, v88, v89
	v_mul_f32_e32 v89, v81, v81
	v_fmac_f32_e32 v89, v80, v80
	v_add_f32_e32 v100, v100, v101
	v_mul_f32_e32 v101, v91, v91
	v_add_f32_e32 v88, v88, v89
	v_mul_f32_e32 v89, v83, v83
	v_fmac_f32_e32 v101, v90, v90
	v_fmac_f32_e32 v89, v82, v82
	v_add_f32_e32 v100, v101, v100
	v_add_f32_e32 v88, v89, v88
	v_cvt_pk_bf16_f32 v95, v90, v91
	v_add_f32_e32 v90, v100, v88
	ds_bpermute_b32 v91, v156, v90
	v_or_b32_e32 v96, 32, v146
	v_ashrrev_i32_e32 v97, 31, v96
	v_lshlrev_b64 v[98:99], 11, v[96:97]
	v_lshl_add_u64 v[88:89], s[66:67], 0, v[98:99]
	v_lshl_add_u64 v[98:99], v[144:145], 0, v[88:89]
	v_cvt_pk_bf16_f32 v88, v84, v85
	s_waitcnt lgkmcnt(0)
	v_add_f32_e32 v84, v90, v91
	ds_bpermute_b32 v85, v155, v84
	v_cvt_pk_bf16_f32 v89, v86, v87
	v_cvt_pk_bf16_f32 v90, v80, v81
	v_cvt_pk_bf16_f32 v91, v82, v83
	global_store_dwordx4 v[98:99], v[92:95], off sc1
	global_store_dwordx4 v[98:99], v[88:91], off offset:1024 sc1
	s_and_saveexec_b64 s[34:35], s[4:5]
	s_cbranch_execz .LBB0_963
	v_lshlrev_b64 v[80:81], 6, v[96:97]
	v_lshl_add_u64 v[80:81], s[0:1], 0, v[80:81]
	v_lshl_add_u64 v[80:81], s[30:31], 2, v[80:81]
	s_lshl_b32 s14, s45, 2
	s_waitcnt lgkmcnt(0)
	v_add_f32_e32 v82, v84, v85
	v_lshl_add_u64 v[80:81], v[80:81], 0, s[14:15]
	global_store_dword v[80:81], v82, off
.LBB0_963:
	s_or_b64 exec, exec, s[34:35]
	v_mul_f32_e32 v84, v77, v77
	s_waitcnt lgkmcnt(0)
	v_mul_f32_e32 v85, v79, v79
	v_fmac_f32_e32 v84, v76, v76
	v_fmac_f32_e32 v85, v78, v78
	v_add_f32_e32 v84, v84, v85
	v_mul_f32_e32 v85, v73, v73
	v_fmac_f32_e32 v85, v72, v72
	v_cvt_pk_bf16_f32 v76, v76, v77
	v_cvt_pk_bf16_f32 v77, v78, v79
	v_cvt_pk_bf16_f32 v78, v72, v73
	v_mul_f32_e32 v72, v69, v69
	v_mul_f32_e32 v73, v71, v71
	v_fmac_f32_e32 v72, v68, v68
	v_fmac_f32_e32 v73, v70, v70
	v_add_f32_e32 v72, v72, v73
	v_mul_f32_e32 v73, v65, v65
	v_fmac_f32_e32 v73, v64, v64
	v_add_f32_e32 v84, v84, v85
	v_mul_f32_e32 v85, v75, v75
	v_add_f32_e32 v72, v72, v73
	v_mul_f32_e32 v73, v67, v67
	v_fmac_f32_e32 v85, v74, v74
	v_fmac_f32_e32 v73, v66, v66
	v_add_f32_e32 v84, v85, v84
	v_add_f32_e32 v72, v73, v72
	v_cvt_pk_bf16_f32 v79, v74, v75
	v_add_f32_e32 v74, v84, v72
	ds_bpermute_b32 v75, v156, v74
	v_or_b32_e32 v80, 48, v146
	v_ashrrev_i32_e32 v81, 31, v80
	v_lshlrev_b64 v[82:83], 11, v[80:81]
	v_lshl_add_u64 v[72:73], s[66:67], 0, v[82:83]
	v_lshl_add_u64 v[82:83], v[144:145], 0, v[72:73]
	v_cvt_pk_bf16_f32 v72, v68, v69
	s_waitcnt lgkmcnt(0)
	v_add_f32_e32 v68, v74, v75
	ds_bpermute_b32 v69, v155, v68
	v_cvt_pk_bf16_f32 v73, v70, v71
	v_cvt_pk_bf16_f32 v74, v64, v65
	v_cvt_pk_bf16_f32 v75, v66, v67
	global_store_dwordx4 v[82:83], v[76:79], off sc1
	global_store_dwordx4 v[82:83], v[72:75], off offset:1024 sc1
	s_and_saveexec_b64 s[34:35], s[4:5]
	s_cbranch_execz .LBB0_965
	v_lshlrev_b64 v[64:65], 6, v[80:81]
	v_lshl_add_u64 v[64:65], s[0:1], 0, v[64:65]
	v_lshl_add_u64 v[64:65], s[30:31], 2, v[64:65]
	s_lshl_b32 s14, s45, 2
	s_waitcnt lgkmcnt(0)
	v_add_f32_e32 v66, v68, v69
	v_lshl_add_u64 v[64:65], v[64:65], 0, s[14:15]
	global_store_dword v[64:65], v66, off
.LBB0_965:
	s_or_b64 exec, exec, s[34:35]
	v_mul_f32_e32 v68, v61, v61
	s_waitcnt lgkmcnt(0)
	v_mul_f32_e32 v69, v63, v63
	v_fmac_f32_e32 v68, v60, v60
	v_fmac_f32_e32 v69, v62, v62
	v_add_f32_e32 v68, v68, v69
	v_mul_f32_e32 v69, v57, v57
	v_fmac_f32_e32 v69, v56, v56
	v_cvt_pk_bf16_f32 v60, v60, v61
	v_cvt_pk_bf16_f32 v61, v62, v63
	v_cvt_pk_bf16_f32 v62, v56, v57
	v_mul_f32_e32 v56, v53, v53
	v_mul_f32_e32 v57, v55, v55
	v_fmac_f32_e32 v56, v52, v52
	v_fmac_f32_e32 v57, v54, v54
	v_add_f32_e32 v56, v56, v57
	v_mul_f32_e32 v57, v49, v49
	v_fmac_f32_e32 v57, v48, v48
	v_add_f32_e32 v68, v68, v69
	v_mul_f32_e32 v69, v59, v59
	v_add_f32_e32 v56, v56, v57
	v_mul_f32_e32 v57, v51, v51
	v_fmac_f32_e32 v69, v58, v58
	v_fmac_f32_e32 v57, v50, v50
	v_add_f32_e32 v68, v69, v68
	v_add_f32_e32 v56, v57, v56
	v_cvt_pk_bf16_f32 v63, v58, v59
	v_add_f32_e32 v58, v68, v56
	ds_bpermute_b32 v59, v156, v58
	v_add_u32_e32 v64, 0x80, v146
	v_ashrrev_i32_e32 v65, 31, v64
	v_lshlrev_b64 v[66:67], 11, v[64:65]
	v_lshl_add_u64 v[56:57], s[66:67], 0, v[66:67]
	v_lshl_add_u64 v[66:67], v[144:145], 0, v[56:57]
	v_cvt_pk_bf16_f32 v56, v52, v53
	s_waitcnt lgkmcnt(0)
	v_add_f32_e32 v52, v58, v59
	ds_bpermute_b32 v53, v155, v52
	v_cvt_pk_bf16_f32 v57, v54, v55
	v_cvt_pk_bf16_f32 v58, v48, v49
	v_cvt_pk_bf16_f32 v59, v50, v51
	global_store_dwordx4 v[66:67], v[60:63], off sc1
	global_store_dwordx4 v[66:67], v[56:59], off offset:1024 sc1
	s_and_saveexec_b64 s[34:35], s[4:5]
	s_cbranch_execz .LBB0_967
	v_lshlrev_b64 v[48:49], 6, v[64:65]
	v_lshl_add_u64 v[48:49], s[0:1], 0, v[48:49]
	v_lshl_add_u64 v[48:49], s[30:31], 2, v[48:49]
	s_lshl_b32 s14, s45, 2
	s_waitcnt lgkmcnt(0)
	v_add_f32_e32 v50, v52, v53
	v_lshl_add_u64 v[48:49], v[48:49], 0, s[14:15]
	global_store_dword v[48:49], v50, off
.LBB0_967:
	s_or_b64 exec, exec, s[34:35]
	v_mul_f32_e32 v52, v45, v45
	s_waitcnt lgkmcnt(0)
	v_mul_f32_e32 v53, v47, v47
	v_fmac_f32_e32 v52, v44, v44
	v_fmac_f32_e32 v53, v46, v46
	v_add_f32_e32 v52, v52, v53
	v_mul_f32_e32 v53, v41, v41
	v_fmac_f32_e32 v53, v40, v40
	v_cvt_pk_bf16_f32 v44, v44, v45
	v_cvt_pk_bf16_f32 v45, v46, v47
	v_cvt_pk_bf16_f32 v46, v40, v41
	v_mul_f32_e32 v40, v37, v37
	v_mul_f32_e32 v41, v39, v39
	v_fmac_f32_e32 v40, v36, v36
	v_fmac_f32_e32 v41, v38, v38
	v_add_f32_e32 v40, v40, v41
	v_mul_f32_e32 v41, v33, v33
	v_fmac_f32_e32 v41, v32, v32
	v_add_f32_e32 v52, v52, v53
	v_mul_f32_e32 v53, v43, v43
	v_add_f32_e32 v40, v40, v41
	v_mul_f32_e32 v41, v35, v35
	v_fmac_f32_e32 v53, v42, v42
	v_fmac_f32_e32 v41, v34, v34
	v_add_f32_e32 v52, v53, v52
	v_add_f32_e32 v40, v41, v40
	v_cvt_pk_bf16_f32 v47, v42, v43
	v_add_f32_e32 v42, v52, v40
	ds_bpermute_b32 v43, v156, v42
	v_add_u32_e32 v48, 0x90, v146
	v_ashrrev_i32_e32 v49, 31, v48
	v_lshlrev_b64 v[50:51], 11, v[48:49]
	v_lshl_add_u64 v[40:41], s[66:67], 0, v[50:51]
	v_lshl_add_u64 v[50:51], v[144:145], 0, v[40:41]
	v_cvt_pk_bf16_f32 v40, v36, v37
	s_waitcnt lgkmcnt(0)
	v_add_f32_e32 v36, v42, v43
	ds_bpermute_b32 v37, v155, v36
	v_cvt_pk_bf16_f32 v41, v38, v39
	v_cvt_pk_bf16_f32 v42, v32, v33
	v_cvt_pk_bf16_f32 v43, v34, v35
	global_store_dwordx4 v[50:51], v[44:47], off sc1
	global_store_dwordx4 v[50:51], v[40:43], off offset:1024 sc1
	s_and_saveexec_b64 s[34:35], s[4:5]
	s_cbranch_execz .LBB0_969
	v_lshlrev_b64 v[32:33], 6, v[48:49]
	v_lshl_add_u64 v[32:33], s[0:1], 0, v[32:33]
	v_lshl_add_u64 v[32:33], s[30:31], 2, v[32:33]
	s_lshl_b32 s14, s45, 2
	s_waitcnt lgkmcnt(0)
	v_add_f32_e32 v34, v36, v37
	v_lshl_add_u64 v[32:33], v[32:33], 0, s[14:15]
	global_store_dword v[32:33], v34, off
.LBB0_969:
	s_or_b64 exec, exec, s[34:35]
	v_mul_f32_e32 v36, v29, v29
	s_waitcnt lgkmcnt(0)
	v_mul_f32_e32 v37, v31, v31
	v_fmac_f32_e32 v36, v28, v28
	v_fmac_f32_e32 v37, v30, v30
	v_add_f32_e32 v36, v36, v37
	v_mul_f32_e32 v37, v25, v25
	v_fmac_f32_e32 v37, v24, v24
	v_cvt_pk_bf16_f32 v28, v28, v29
	v_cvt_pk_bf16_f32 v29, v30, v31
	v_cvt_pk_bf16_f32 v30, v24, v25
	v_mul_f32_e32 v24, v21, v21
	v_mul_f32_e32 v25, v23, v23
	v_fmac_f32_e32 v24, v20, v20
	v_fmac_f32_e32 v25, v22, v22
	v_add_f32_e32 v24, v24, v25
	v_mul_f32_e32 v25, v17, v17
	v_fmac_f32_e32 v25, v16, v16
	v_add_f32_e32 v36, v36, v37
	v_mul_f32_e32 v37, v27, v27
	v_add_f32_e32 v24, v24, v25
	v_mul_f32_e32 v25, v19, v19
	v_fmac_f32_e32 v37, v26, v26
	v_fmac_f32_e32 v25, v18, v18
	v_add_f32_e32 v36, v37, v36
	v_add_f32_e32 v24, v25, v24
	v_cvt_pk_bf16_f32 v31, v26, v27
	v_add_f32_e32 v26, v36, v24
	ds_bpermute_b32 v27, v156, v26
	v_add_u32_e32 v32, 0xa0, v146
	v_ashrrev_i32_e32 v33, 31, v32
	v_lshlrev_b64 v[34:35], 11, v[32:33]
	v_lshl_add_u64 v[24:25], s[66:67], 0, v[34:35]
	v_lshl_add_u64 v[34:35], v[144:145], 0, v[24:25]
	v_cvt_pk_bf16_f32 v24, v20, v21
	s_waitcnt lgkmcnt(0)
	v_add_f32_e32 v20, v26, v27
	ds_bpermute_b32 v21, v155, v20
	v_cvt_pk_bf16_f32 v25, v22, v23
	v_cvt_pk_bf16_f32 v26, v16, v17
	v_cvt_pk_bf16_f32 v27, v18, v19
	global_store_dwordx4 v[34:35], v[28:31], off sc1
	global_store_dwordx4 v[34:35], v[24:27], off offset:1024 sc1
	s_and_saveexec_b64 s[34:35], s[4:5]
	s_cbranch_execz .LBB0_971
	v_lshlrev_b64 v[16:17], 6, v[32:33]
	v_lshl_add_u64 v[16:17], s[0:1], 0, v[16:17]
	v_lshl_add_u64 v[16:17], s[30:31], 2, v[16:17]
	s_lshl_b32 s14, s45, 2
	s_waitcnt lgkmcnt(0)
	v_add_f32_e32 v18, v20, v21
	v_lshl_add_u64 v[16:17], v[16:17], 0, s[14:15]
	global_store_dword v[16:17], v18, off
.LBB0_971:
	s_or_b64 exec, exec, s[34:35]
	v_mul_f32_e32 v20, v13, v13
	s_waitcnt lgkmcnt(0)
	v_mul_f32_e32 v21, v15, v15
	v_fmac_f32_e32 v20, v12, v12
	v_fmac_f32_e32 v21, v14, v14
	v_add_f32_e32 v20, v20, v21
	v_mul_f32_e32 v21, v9, v9
	v_fmac_f32_e32 v21, v8, v8
	v_cvt_pk_bf16_f32 v12, v12, v13
	v_cvt_pk_bf16_f32 v13, v14, v15
	v_cvt_pk_bf16_f32 v14, v8, v9
	v_mul_f32_e32 v8, v5, v5
	v_mul_f32_e32 v9, v7, v7
	v_fmac_f32_e32 v8, v4, v4
	v_fmac_f32_e32 v9, v6, v6
	v_add_f32_e32 v8, v8, v9
	v_mul_f32_e32 v9, v1, v1
	v_fmac_f32_e32 v9, v0, v0
	v_add_f32_e32 v20, v20, v21
	v_mul_f32_e32 v21, v11, v11
	v_add_f32_e32 v8, v8, v9
	v_mul_f32_e32 v9, v3, v3
	v_fmac_f32_e32 v21, v10, v10
	v_fmac_f32_e32 v9, v2, v2
	v_add_f32_e32 v20, v21, v20
	v_add_f32_e32 v8, v9, v8
	v_cvt_pk_bf16_f32 v15, v10, v11
	v_add_f32_e32 v10, v20, v8
	ds_bpermute_b32 v11, v156, v10
	v_add_u32_e32 v16, 0xb0, v146
	v_ashrrev_i32_e32 v17, 31, v16
	v_lshlrev_b64 v[18:19], 11, v[16:17]
	v_lshl_add_u64 v[8:9], s[66:67], 0, v[18:19]
	v_lshl_add_u64 v[18:19], v[144:145], 0, v[8:9]
	v_cvt_pk_bf16_f32 v8, v4, v5
	s_waitcnt lgkmcnt(0)
	v_add_f32_e32 v4, v10, v11
	ds_bpermute_b32 v5, v155, v4
	v_cvt_pk_bf16_f32 v9, v6, v7
	v_cvt_pk_bf16_f32 v10, v0, v1
	v_cvt_pk_bf16_f32 v11, v2, v3
	global_store_dwordx4 v[18:19], v[12:15], off sc1
	global_store_dwordx4 v[18:19], v[8:11], off offset:1024 sc1
	s_and_saveexec_b64 s[34:35], s[4:5]
	s_cbranch_execz .LBB0_973
	v_lshlrev_b64 v[0:1], 6, v[16:17]
	v_lshl_add_u64 v[0:1], s[0:1], 0, v[0:1]
	v_lshl_add_u64 v[0:1], s[30:31], 2, v[0:1]
	s_lshl_b32 s14, s45, 2
	s_waitcnt lgkmcnt(0)
	v_add_f32_e32 v2, v4, v5
	v_lshl_add_u64 v[0:1], v[0:1], 0, s[14:15]
	global_store_dword v[0:1], v2, off

.LBB0_1031:
	s_cmp_lt_i32 s90, 11
	s_cselect_b64 s[6:7], -1, 0
	s_and_b64 s[4:5], s[6:7], s[4:5]
	s_andn2_b64 vcc, exec, s[4:5]
	s_cbranch_vccnz .LBB0_1037
	s_lshl_b32 s2, s2, 3
	s_add_i32 s4, s94, s2
	s_cmpk_gt_i32 s4, 0x7fff
	s_cbranch_scc1 .LBB0_1037
	v_readlane_b32 s16, v254, 3
	s_waitcnt vmcnt(0)
	v_lshlrev_b32_e32 v32, 4, v221
	v_readlane_b32 s20, v254, 7
	v_readlane_b32 s21, v254, 8
	global_load_dwordx4 v[0:3], v32, s[80:81] offset:3072
	s_waitcnt lgkmcnt(0)
	global_load_dwordx4 v[4:7], v32, s[80:81] offset:2048
	s_nop 1
	global_load_dwordx4 v[8:11], v32, s[20:21] offset:3072
	global_load_dwordx4 v[12:15], v32, s[20:21] offset:2048
	global_load_dwordx4 v[16:19], v32, s[80:81] offset:1024
	global_load_dwordx4 v[20:23], v32, s[80:81]
	global_load_dwordx4 v[24:27], v32, s[20:21] offset:1024
	global_load_dwordx4 v[28:31], v32, s[20:21]
	v_mov_b32_e32 v33, 0
	v_and_b32_e32 v34, 3, v220
	v_lshlrev_b32_e32 v34, 4, v34
	v_mov_b32_e32 v35, v33
	v_lshl_add_u64 v[52:53], s[10:11], 0, v[34:35]
	v_lshl_add_u64 v[54:55], s[0:1], 0, v[34:35]
	v_mbcnt_lo_u32_b32 v34, -1, 0
	v_mbcnt_hi_u32_b32 v34, -1, v34
	v_and_b32_e32 v36, 64, v34
	v_xor_b32_e32 v35, 1, v34
	v_add_u32_e32 v36, 64, v36
	v_cmp_lt_i32_e32 vcc, v35, v36
	v_readlane_b32 s17, v254, 4
	s_lshl_b32 s12, s92, 3
	v_cndmask_b32_e32 v35, v34, v35, vcc
	v_lshlrev_b32_e32 v84, 2, v35
	v_xor_b32_e32 v35, 2, v34
	v_cmp_lt_i32_e32 vcc, v35, v36
	v_lshl_add_u64 v[56:57], s[16:17], 0, v[32:33]
	v_lshl_add_u64 v[62:63], s[86:87], 0, v[32:33]
	v_cndmask_b32_e32 v34, v34, v35, vcc
	v_lshlrev_b32_e32 v85, 2, v34
	v_bfe_u32 v60, v221, 4, 1
	v_lshlrev_b32_e32 v60, 13, v60
	v_lshrrev_b32_e32 v61, 5, v221
	v_lshl_or_b32 v60, v61, 10, v60
	v_and_b32_e32 v61, 15, v221
	v_lshl_or_b32 v60, v61, 3, v60
	v_add_u32_e32 v34, 0x1000, v60
	v_mov_b32_e32 v35, v33
	v_lshl_add_u64 v[58:59], s[8:9], 0, v[34:35]
	v_lshl_add_u64 v[60:61], s[66:67], 0, v[34:35]
	s_lshl_b32 s10, s92, 4
	v_mov_b32_e32 v86, 0x358637bd
	s_mov_b32 s11, 0xf800000
	v_mov_b32_e32 v87, 0x260
	v_readlane_b32 s18, v254, 5
	v_readlane_b32 s19, v254, 6
	v_readlane_b32 s22, v254, 9
	v_readlane_b32 s23, v254, 10
	v_readlane_b32 s24, v254, 11
	v_readlane_b32 s25, v254, 12
	v_readlane_b32 s26, v254, 13
	v_readlane_b32 s27, v254, 14
	v_readlane_b32 s28, v254, 15
	v_readlane_b32 s29, v254, 16
	v_readlane_b32 s30, v254, 17
	v_readlane_b32 s31, v254, 18
	s_branch .LBB0_1035

.LBB0_1035:
	s_ashr_i32 s5, s4, 31
	s_lshl_b64 s[0:1], s[4:5], 6
	s_waitcnt vmcnt(12)
	v_lshl_add_u64 v[32:33], v[52:53], 0, s[0:1]
	s_waitcnt lgkmcnt(0)
	global_load_dwordx4 v[88:91], v[32:33], off
	v_lshl_add_u64 v[32:33], v[54:55], 0, s[0:1]
	global_load_dwordx4 v[92:95], v[32:33], off
	s_add_i32 s6, s12, s4
	s_cmp_lt_i32 s6, 0x8000
	s_cselect_b32 s0, s6, s4
	s_ashr_i32 s1, s0, 31
	s_lshl_b64 s[2:3], s[0:1], 6
	v_lshl_add_u64 v[32:33], v[52:53], 0, s[2:3]
	global_load_dwordx4 v[96:99], v[32:33], off
	v_lshl_add_u64 v[32:33], v[54:55], 0, s[2:3]
	global_load_dwordx4 v[100:103], v[32:33], off
	s_lshl_b64 s[8:9], s[4:5], 12
	s_lshr_b32 s2, s4, 3
	s_lshl_b32 s2, s2, 14
	s_and_b32 s3, s4, 7
	s_lshl_b32 s3, s3, 7
	s_add_u32 s2, s2, s3
	s_mov_b32 s3, 0
	v_lshl_add_u64 v[36:37], v[56:57], 0, s[8:9]
	v_lshl_add_u64 v[32:33], v[60:61], 0, s[2:3]
	v_lshl_add_u64 v[34:35], v[58:59], 0, s[2:3]
	global_load_dwordx4 v[48:51], v[36:37], off offset:3072 nt
	global_load_dwordx4 v[104:107], v[36:37], off offset:2048 nt
	global_load_dwordx2 v[80:81], v[32:33], off offset:2048 nt
	global_load_dwordx2 v[116:117], v[32:33], off nt
	global_load_dwordx2 v[118:119], v[32:33], off offset:-2048 nt
	global_load_dwordx2 v[120:121], v[32:33], off offset:-4096 nt
	global_load_dwordx2 v[82:83], v[34:35], off offset:2048 nt
	global_load_dwordx2 v[122:123], v[34:35], off nt
	global_load_dwordx2 v[124:125], v[34:35], off offset:-2048 nt
	global_load_dwordx2 v[126:127], v[34:35], off offset:-4096 nt
	global_load_dwordx4 v[108:111], v[36:37], off offset:1024 nt
	global_load_dwordx4 v[112:115], v[36:37], off nt
	s_lshl_b64 s[2:3], s[0:1], 12
	s_and_b32 s1, s0, 7
	s_lshl_b32 s1, s1, 7
	s_lshr_b32 s0, s0, 3
	s_lshl_b32 s0, s0, 14
	s_add_u32 s0, s0, s1
	s_mov_b32 s1, 0
	s_waitcnt vmcnt(20)
	v_lshl_add_u64 v[64:65], v[56:57], 0, s[2:3]
	v_lshl_add_u64 v[68:69], v[58:59], 0, s[0:1]
	v_lshl_add_u64 v[128:129], v[60:61], 0, s[0:1]
	global_load_dwordx4 v[44:47], v[64:65], off nt
	global_load_dwordx4 v[40:43], v[64:65], off offset:1024 nt
	global_load_dwordx4 v[36:39], v[64:65], off offset:2048 nt
	global_load_dwordx4 v[32:35], v[64:65], off offset:3072 nt
	global_load_dwordx2 v[78:79], v[68:69], off offset:-4096 nt
	global_load_dwordx2 v[74:75], v[68:69], off offset:-2048 nt
	global_load_dwordx2 v[70:71], v[68:69], off nt
	global_load_dwordx2 v[66:67], v[68:69], off offset:2048 nt
	global_load_dwordx2 v[76:77], v[128:129], off offset:-4096 nt
	global_load_dwordx2 v[72:73], v[128:129], off offset:-2048 nt
	s_nop 0
	global_load_dwordx2 v[68:69], v[128:129], off nt
	global_load_dwordx2 v[64:65], v[128:129], off offset:2048 nt
	s_cmpk_gt_i32 s6, 0x7fff
	s_waitcnt vmcnt(27)
	v_mov_b32_e32 v128, v89
	v_mov_b32_e32 v129, v90
	v_mov_b32_e32 v89, v91
	s_waitcnt vmcnt(26)
	v_mov_b32_e32 v90, v93
	v_mov_b32_e32 v91, v94
	v_mov_b32_e32 v93, v95
	v_pk_add_f32 v[88:89], v[128:129], v[88:89]
	v_pk_add_f32 v[90:91], v[90:91], v[92:93]
	v_add_f32_e32 v88, v88, v89
	v_add_f32_e32 v89, v90, v91
	ds_bpermute_b32 v91, v84, v89
	ds_bpermute_b32 v90, v84, v88
	s_waitcnt vmcnt(25)
	v_add_f32_e32 v92, v96, v97
	v_add_f32_e32 v93, v98, v99
	s_waitcnt vmcnt(24)
	v_add_f32_e32 v94, v100, v101
	s_waitcnt lgkmcnt(1)
	v_add_f32_e32 v91, v89, v91
	v_add_f32_e32 v95, v102, v103
	v_add_f32_e32 v92, v92, v93
	s_waitcnt lgkmcnt(0)
	v_add_f32_e32 v96, v88, v90
	ds_bpermute_b32 v97, v85, v91
	v_add_f32_e32 v93, v94, v95
	ds_bpermute_b32 v94, v84, v92
	ds_bpermute_b32 v98, v85, v96
	ds_bpermute_b32 v95, v84, v93
	s_waitcnt lgkmcnt(3)
	v_add_f32_e32 v91, v91, v97
	v_fmamk_f32 v91, v91, 0x3a800000, v86
	s_waitcnt lgkmcnt(2)
	v_add_f32_e32 v88, v92, v94
	s_waitcnt lgkmcnt(1)
	v_add_f32_e32 v92, v96, v98
	s_waitcnt lgkmcnt(0)
	v_add_f32_e32 v90, v93, v95
	v_fmamk_f32 v92, v92, 0x3a800000, v86
	v_mul_f32_e32 v93, 0x4f800000, v91
	v_cmp_gt_f32_e32 vcc, s11, v91
	v_mul_f32_e32 v94, 0x4f800000, v92
	v_cmp_gt_f32_e64 s[0:1], s11, v92
	v_cndmask_b32_e32 v93, v91, v93, vcc
	v_sqrt_f32_e32 v95, v93
	v_cndmask_b32_e64 v92, v92, v94, s[0:1]
	v_sqrt_f32_e32 v94, v92
	ds_bpermute_b32 v89, v85, v88
	v_add_u32_e32 v96, -1, v95
	v_fma_f32 v100, -v96, v95, v93
	v_add_u32_e32 v98, -1, v94
	v_add_u32_e32 v97, 1, v95
	v_fma_f32 v102, -v98, v94, v92
	v_cmp_ge_f32_e64 s[2:3], 0, v100
	v_add_u32_e32 v99, 1, v94
	v_fma_f32 v101, -v97, v95, v93
	v_cndmask_b32_e64 v95, v95, v96, s[2:3]
	v_cmp_ge_f32_e64 s[2:3], 0, v102
	v_fma_f32 v103, -v99, v94, v92
	s_waitcnt vmcnt(18)
	v_lshlrev_b32_e32 v102, 16, v121
	v_cndmask_b32_e64 v94, v94, v98, s[2:3]
	v_cmp_lt_f32_e64 s[2:3], 0, v101
	v_lshl_add_u64 v[100:101], v[62:63], 0, s[8:9]
	ds_bpermute_b32 v91, v85, v90
	v_cndmask_b32_e64 v95, v95, v97, s[2:3]
	v_mul_f32_e32 v96, 0x37800000, v95
	v_cndmask_b32_e32 v95, v95, v96, vcc
	v_cmp_class_f32_e32 vcc, v93, v87
	v_cmp_lt_f32_e64 s[2:3], 0, v103
	v_and_b32_e32 v103, 0xffff0000, v121
	v_cndmask_b32_e32 v93, v95, v93, vcc
	v_cndmask_b32_e64 v94, v94, v99, s[2:3]
	v_div_scale_f32 v95, s[2:3], v93, v93, 1.0
	v_rcp_f32_e32 v96, v95
	v_mul_f32_e32 v97, 0x37800000, v94
	v_cndmask_b32_e64 v94, v94, v97, s[0:1]
	v_div_scale_f32 v97, vcc, 1.0, v93, 1.0
	v_fma_f32 v98, -v95, v96, 1.0
	v_fmac_f32_e32 v96, v98, v96
	v_mul_f32_e32 v98, v97, v96
	v_cmp_class_f32_e64 s[0:1], v92, v87
	v_fma_f32 v99, -v95, v98, v97
	v_fmac_f32_e32 v98, v99, v96
	v_cndmask_b32_e64 v92, v94, v92, s[0:1]
	v_div_scale_f32 v94, s[0:1], v92, v92, 1.0
	v_fma_f32 v95, -v95, v98, v97
	v_rcp_f32_e32 v97, v94
	v_div_fmas_f32 v95, v95, v96, v98
	v_div_fixup_f32 v96, v95, v93, 1.0
	v_fma_f32 v93, -v94, v97, 1.0
	v_fmac_f32_e32 v97, v93, v97
	v_div_scale_f32 v93, vcc, 1.0, v92, 1.0
	v_mul_f32_e32 v95, v93, v97
	v_fma_f32 v98, -v94, v95, v93
	v_fmac_f32_e32 v95, v98, v97
	v_fma_f32 v93, -v94, v95, v93
	v_div_fmas_f32 v93, v93, v97, v95
	v_div_fixup_f32 v98, v93, v92, 1.0
	s_waitcnt vmcnt(14)
	v_lshlrev_b32_e32 v92, 16, v126
	v_and_b32_e32 v93, 0xffff0000, v126
	v_pk_mul_f32 v[92:93], v[98:99], v[92:93] op_sel_hi:[0,1]
	v_lshlrev_b32_e32 v94, 16, v120
	v_and_b32_e32 v95, 0xffff0000, v120
	s_waitcnt vmcnt(12)
	v_pk_fma_f32 v[92:93], v[28:29], v[92:93], v[112:113]
	v_pk_mul_f32 v[94:95], v[96:97], v[94:95] op_sel_hi:[0,1]
	v_pk_fma_f32 v[92:93], v[20:21], v[94:95], v[92:93]
	v_lshlrev_b32_e32 v94, 16, v127
	v_and_b32_e32 v95, 0xffff0000, v127
	v_pk_mul_f32 v[94:95], v[98:99], v[94:95] op_sel_hi:[0,1]
	v_pk_fma_f32 v[94:95], v[30:31], v[94:95], v[114:115]
	v_pk_mul_f32 v[102:103], v[96:97], v[102:103] op_sel_hi:[0,1]
	v_pk_fma_f32 v[94:95], v[22:23], v[102:103], v[94:95]
	global_store_dwordx4 v[100:101], v[92:95], off nt
	v_lshlrev_b32_e32 v102, 16, v119
	v_and_b32_e32 v103, 0xffff0000, v119
	v_lshlrev_b32_e32 v92, 16, v124
	v_and_b32_e32 v93, 0xffff0000, v124
	v_pk_mul_f32 v[92:93], v[98:99], v[92:93] op_sel_hi:[0,1]
	v_lshlrev_b32_e32 v94, 16, v118
	v_and_b32_e32 v95, 0xffff0000, v118
	v_pk_fma_f32 v[92:93], v[24:25], v[92:93], v[108:109]
	v_pk_mul_f32 v[94:95], v[96:97], v[94:95] op_sel_hi:[0,1]
	v_pk_fma_f32 v[92:93], v[16:17], v[94:95], v[92:93]
	v_lshlrev_b32_e32 v94, 16, v125
	v_and_b32_e32 v95, 0xffff0000, v125
	v_pk_mul_f32 v[94:95], v[98:99], v[94:95] op_sel_hi:[0,1]
	v_pk_fma_f32 v[94:95], v[26:27], v[94:95], v[110:111]
	v_pk_mul_f32 v[102:103], v[96:97], v[102:103] op_sel_hi:[0,1]
	v_pk_fma_f32 v[94:95], v[18:19], v[102:103], v[94:95]
	global_store_dwordx4 v[100:101], v[92:95], off offset:1024 nt
	v_lshlrev_b32_e32 v102, 16, v117
	v_and_b32_e32 v103, 0xffff0000, v117
	v_lshlrev_b32_e32 v92, 16, v122
	v_and_b32_e32 v93, 0xffff0000, v122
	v_pk_mul_f32 v[92:93], v[98:99], v[92:93] op_sel_hi:[0,1]
	v_lshlrev_b32_e32 v94, 16, v116
	v_and_b32_e32 v95, 0xffff0000, v116
	v_pk_fma_f32 v[92:93], v[12:13], v[92:93], v[104:105]
	v_pk_mul_f32 v[94:95], v[96:97], v[94:95] op_sel_hi:[0,1]
	v_pk_fma_f32 v[92:93], v[4:5], v[94:95], v[92:93]
	v_lshlrev_b32_e32 v94, 16, v123
	v_and_b32_e32 v95, 0xffff0000, v123
	v_pk_mul_f32 v[94:95], v[98:99], v[94:95] op_sel_hi:[0,1]
	v_pk_fma_f32 v[94:95], v[14:15], v[94:95], v[106:107]
	v_pk_mul_f32 v[102:103], v[96:97], v[102:103] op_sel_hi:[0,1]
	v_pk_fma_f32 v[94:95], v[6:7], v[102:103], v[94:95]
	global_store_dwordx4 v[100:101], v[92:95], off offset:2048 nt
	s_nop 1
	v_lshlrev_b32_e32 v92, 16, v82
	v_and_b32_e32 v93, 0xffff0000, v82
	v_pk_mul_f32 v[92:93], v[98:99], v[92:93] op_sel_hi:[0,1]
	v_lshlrev_b32_e32 v82, 16, v83
	v_and_b32_e32 v83, 0xffff0000, v83
	v_pk_fma_f32 v[48:49], v[8:9], v[92:93], v[48:49]
	v_lshlrev_b32_e32 v92, 16, v80
	v_and_b32_e32 v93, 0xffff0000, v80
	v_pk_mul_f32 v[82:83], v[98:99], v[82:83] op_sel_hi:[0,1]
	v_lshlrev_b32_e32 v80, 16, v81
	v_and_b32_e32 v81, 0xffff0000, v81
	v_pk_mul_f32 v[92:93], v[96:97], v[92:93] op_sel_hi:[0,1]
	v_pk_fma_f32 v[50:51], v[10:11], v[82:83], v[50:51]
	v_pk_mul_f32 v[80:81], v[96:97], v[80:81] op_sel_hi:[0,1]
	v_pk_fma_f32 v[48:49], v[0:1], v[92:93], v[48:49]
	v_pk_fma_f32 v[50:51], v[2:3], v[80:81], v[50:51]
	global_store_dwordx4 v[100:101], v[48:51], off offset:3072 nt
	s_cbranch_scc1 .LBB0_1034
	s_waitcnt lgkmcnt(0)
	v_add_f32_e32 v48, v90, v91
	v_fmamk_f32 v48, v48, 0x3a800000, v86
	v_mul_f32_e32 v49, 0x4f800000, v48
	v_cmp_gt_f32_e32 vcc, s11, v48
	v_add_f32_e32 v81, v88, v89
	v_fmamk_f32 v81, v81, 0x3a800000, v86
	v_cndmask_b32_e32 v48, v48, v49, vcc
	v_sqrt_f32_e32 v49, v48
	v_mul_f32_e32 v82, 0x4f800000, v81
	s_ashr_i32 s7, s6, 31
	v_add_u32_e32 v50, -1, v49
	v_fma_f32 v80, -v50, v49, v48
	v_add_u32_e32 v51, 1, v49
	v_cmp_ge_f32_e64 s[0:1], 0, v80
	s_nop 1
	v_cndmask_b32_e64 v50, v49, v50, s[0:1]
	v_fma_f32 v49, -v51, v49, v48
	v_cmp_lt_f32_e64 s[0:1], 0, v49
	s_nop 1
	v_cndmask_b32_e64 v49, v50, v51, s[0:1]
	v_mul_f32_e32 v50, 0x37800000, v49
	v_cndmask_b32_e32 v49, v49, v50, vcc
	v_cmp_class_f32_e32 vcc, v48, v87
	s_nop 1
	v_cndmask_b32_e32 v48, v49, v48, vcc
	v_div_scale_f32 v49, s[0:1], v48, v48, 1.0
	v_rcp_f32_e32 v50, v49
	v_cmp_gt_f32_e64 s[0:1], s11, v81
	v_fma_f32 v51, -v49, v50, 1.0
	s_nop 0
	v_cndmask_b32_e64 v81, v81, v82, s[0:1]
	v_fmac_f32_e32 v50, v51, v50
	v_div_scale_f32 v51, vcc, 1.0, v48, 1.0
	v_sqrt_f32_e32 v82, v81
	v_mul_f32_e32 v80, v51, v50
	v_fma_f32 v83, -v49, v80, v51
	v_fmac_f32_e32 v80, v83, v50
	v_fma_f32 v49, -v49, v80, v51
	v_add_u32_e32 v51, -1, v82
	v_fma_f32 v83, -v51, v82, v81
	v_cmp_ge_f32_e64 s[2:3], 0, v83
	v_add_u32_e32 v83, 1, v82
	v_div_fmas_f32 v49, v49, v50, v80
	v_cndmask_b32_e64 v51, v82, v51, s[2:3]
	v_fma_f32 v82, -v83, v82, v81
	v_cmp_lt_f32_e64 s[2:3], 0, v82
	v_div_fixup_f32 v48, v49, v48, 1.0
	s_nop 0
	v_cndmask_b32_e64 v51, v51, v83, s[2:3]
	v_mul_f32_e32 v82, 0x37800000, v51
	v_cndmask_b32_e64 v51, v51, v82, s[0:1]
	v_cmp_class_f32_e64 s[0:1], v81, v87
	s_waitcnt vmcnt(11)
	v_and_b32_e32 v83, 0xffff0000, v78
	v_cndmask_b32_e64 v51, v51, v81, s[0:1]
	v_div_scale_f32 v81, s[0:1], v51, v51, 1.0
	v_rcp_f32_e32 v82, v81
	s_lshl_b64 s[0:1], s[6:7], 12
	v_fma_f32 v49, -v81, v82, 1.0
	v_fmac_f32_e32 v82, v49, v82
	v_div_scale_f32 v49, vcc, 1.0, v51, 1.0
	v_mul_f32_e32 v50, v49, v82
	v_fma_f32 v80, -v81, v50, v49
	v_fmac_f32_e32 v50, v80, v82
	v_fma_f32 v49, -v81, v50, v49
	v_div_fmas_f32 v49, v49, v82, v50
	v_div_fixup_f32 v50, v49, v51, 1.0
	v_lshlrev_b32_e32 v82, 16, v78
	v_pk_mul_f32 v[82:83], v[50:51], v[82:83] op_sel_hi:[0,1]
	v_lshlrev_b32_e32 v78, 16, v79
	v_and_b32_e32 v79, 0xffff0000, v79
	v_pk_fma_f32 v[44:45], v[28:29], v[82:83], v[44:45]
	s_waitcnt vmcnt(7)
	v_lshlrev_b32_e32 v82, 16, v76
	v_and_b32_e32 v83, 0xffff0000, v76
	v_pk_mul_f32 v[78:79], v[50:51], v[78:79] op_sel_hi:[0,1]
	v_lshlrev_b32_e32 v76, 16, v77
	v_and_b32_e32 v77, 0xffff0000, v77
	v_pk_mul_f32 v[82:83], v[48:49], v[82:83] op_sel_hi:[0,1]
	v_pk_fma_f32 v[46:47], v[30:31], v[78:79], v[46:47]
	v_pk_mul_f32 v[76:77], v[48:49], v[76:77] op_sel_hi:[0,1]
	v_lshl_add_u64 v[80:81], v[62:63], 0, s[0:1]
	v_pk_fma_f32 v[44:45], v[20:21], v[82:83], v[44:45]
	v_pk_fma_f32 v[46:47], v[22:23], v[76:77], v[46:47]
	global_store_dwordx4 v[80:81], v[44:47], off nt
	s_nop 1
	v_lshlrev_b32_e32 v44, 16, v74
	v_and_b32_e32 v45, 0xffff0000, v74
	v_pk_mul_f32 v[44:45], v[50:51], v[44:45] op_sel_hi:[0,1]
	v_pk_fma_f32 v[40:41], v[24:25], v[44:45], v[40:41]
	s_waitcnt vmcnt(7)
	v_lshlrev_b32_e32 v44, 16, v72
	v_and_b32_e32 v45, 0xffff0000, v72
	v_pk_mul_f32 v[44:45], v[48:49], v[44:45] op_sel_hi:[0,1]
	v_pk_fma_f32 v[40:41], v[16:17], v[44:45], v[40:41]
	v_lshlrev_b32_e32 v44, 16, v75
	v_and_b32_e32 v45, 0xffff0000, v75
	v_pk_mul_f32 v[44:45], v[50:51], v[44:45] op_sel_hi:[0,1]
	v_pk_fma_f32 v[42:43], v[26:27], v[44:45], v[42:43]
	v_lshlrev_b32_e32 v44, 16, v73
	v_and_b32_e32 v45, 0xffff0000, v73
	v_pk_mul_f32 v[44:45], v[48:49], v[44:45] op_sel_hi:[0,1]
	v_pk_fma_f32 v[42:43], v[18:19], v[44:45], v[42:43]
	global_store_dwordx4 v[80:81], v[40:43], off offset:1024 nt
	s_nop 1
	v_lshlrev_b32_e32 v40, 16, v70
	v_and_b32_e32 v41, 0xffff0000, v70
	v_pk_mul_f32 v[40:41], v[50:51], v[40:41] op_sel_hi:[0,1]
	v_pk_fma_f32 v[36:37], v[12:13], v[40:41], v[36:37]
	s_waitcnt vmcnt(7)
	v_lshlrev_b32_e32 v40, 16, v68
	v_and_b32_e32 v41, 0xffff0000, v68
	v_pk_mul_f32 v[40:41], v[48:49], v[40:41] op_sel_hi:[0,1]
	v_pk_fma_f32 v[36:37], v[4:5], v[40:41], v[36:37]
	v_lshlrev_b32_e32 v40, 16, v71
	v_and_b32_e32 v41, 0xffff0000, v71
	v_pk_mul_f32 v[40:41], v[50:51], v[40:41] op_sel_hi:[0,1]
	v_pk_fma_f32 v[38:39], v[14:15], v[40:41], v[38:39]
	v_lshlrev_b32_e32 v40, 16, v69
	v_and_b32_e32 v41, 0xffff0000, v69
	v_pk_mul_f32 v[40:41], v[48:49], v[40:41] op_sel_hi:[0,1]
	v_pk_fma_f32 v[38:39], v[6:7], v[40:41], v[38:39]
	global_store_dwordx4 v[80:81], v[36:39], off offset:2048 nt
	s_nop 1
	v_lshlrev_b32_e32 v36, 16, v66
	v_and_b32_e32 v37, 0xffff0000, v66
	v_pk_mul_f32 v[36:37], v[50:51], v[36:37] op_sel_hi:[0,1]
	v_pk_fma_f32 v[32:33], v[8:9], v[36:37], v[32:33]
	s_waitcnt vmcnt(7)
	v_lshlrev_b32_e32 v36, 16, v64
	v_and_b32_e32 v37, 0xffff0000, v64
	v_pk_mul_f32 v[36:37], v[48:49], v[36:37] op_sel_hi:[0,1]
	v_pk_fma_f32 v[32:33], v[0:1], v[36:37], v[32:33]
	v_lshlrev_b32_e32 v36, 16, v67
	v_and_b32_e32 v37, 0xffff0000, v67
	v_pk_mul_f32 v[36:37], v[50:51], v[36:37] op_sel_hi:[0,1]
	v_pk_fma_f32 v[34:35], v[10:11], v[36:37], v[34:35]
	v_lshlrev_b32_e32 v36, 16, v65
	v_and_b32_e32 v37, 0xffff0000, v65
	v_pk_mul_f32 v[36:37], v[48:49], v[36:37] op_sel_hi:[0,1]
	v_pk_fma_f32 v[34:35], v[2:3], v[36:37], v[34:35]
	global_store_dwordx4 v[80:81], v[32:35], off offset:3072 nt
	s_branch .LBB0_1034
